# mixers: RWKV step-loop nops removed, mLSTM chunk loads batched; gemm_down residual epilogue batched; merge gate GEMM + out GEMM K loops with 2 DMA stages in flight; L2 tile remap everywhere
# speedup vs baseline: 1.1308x; 1.0457x over previous
; __device__ __forceinline__ unsigned pack2(float a, float b) { const f32x2n v = {a, b}; const bf16x2n h = __builtin_convertvector(v, bf16x2n); return __builtin_bit_cast(unsigned, h); }
; __device__ void mx_rwkv(const Params& P, int l, int item, char* lds) {
;     ...
;         for (int st = 0; st < 16; ++st) {
;             const int sp = d ? 15 - st : st;
;             const f32x4 a4 = *(const f32x4*)(VA + sp * 64 + j0), wr4 = *(const f32x4*)(VWR + sp * 64 + j0), w4 = *(const f32x4*)(VW + sp * 64 + j0);
;             const f32x4 b4 = *(const f32x4*)(VB + sp * 64 + j0), k4 = *(const f32x4*)(VK + sp * 64 + j0), v4 = *(const f32x4*)(VV + sp * 64 + s * 4);
;             const float br = SC[sp * 2], kr = SC[sp * 2 + 1];
;             float psa[4], py[4];
;             typedef float f32x2 __attribute__((ext_vector_type(2)));
;             const f32x2 a01 = {a4[0], a4[1]}, a23 = {a4[2], a4[3]}, r01 = {wr4[0], wr4[1]}, r23 = {wr4[2], wr4[3]};
; #pragma unroll
;             for (int i = 0; i < 4; ++i) {
;                 const f32x2 s01 = {S[i][0], S[i][1]}, s23 = {S[i][2], S[i][3]};
;                 f32x2 ta = s01 * a01; ta = s23 * a23 + ta;
;                 f32x2 ty = s01 * r01; ty = s23 * r23 + ty;
;                 psa[i] = ta.x + ta.y; py[i] = ty.x + ty.y;
;             }
;     ...
;             RS8("row_ror:8"); RS8("row_ror:4"); RS8("row_ror:2"); RS8("row_ror:1");
;             asm volatile("s_nop 1" ::: "memory");
;             float y[4];
; #pragma unroll
;             for (int i = 0; i < 4; ++i) {
;                 y[i] = py[i] + psa[i] * br + v4[i] * kr;
; #pragma unroll
;                 for (int j = 0; j < 4; ++j) S[i][j] = S[i][j] * w4[j] + (psa[i] * b4[j] + v4[i] * k4[j]);
;             }
;             if (jg == 0) *(u32x2*)(Yd + (size_t)(t0 + sp) * 512 + s * 4) = (u32x2){pack2(y[0], y[1]), pack2(y[2], y[3])};
;         }
.LBB0_253:
	s_and_b64 s[0:1], s[50:51], exec
	s_cselect_b32 s24, s29, s34
	s_lshl_b32 s0, s24, 8
	v_add_u32_e32 v0, s0, v134
	ds_read_b128 v[124:127], v0
	ds_read_b128 v[142:145], v0 offset:4096
	ds_read_b128 v[72:75], v0 offset:8192
	ds_read_b128 v[76:79], v0 offset:12288
	v_add_u32_e32 v2, s0, v98
	ds_read_b128 v[80:83], v0 offset:16384
	ds_read_b128 v[84:87], v2 offset:20480
	s_waitcnt lgkmcnt(5)
	v_pk_mul_f32 v[2:3], v[110:111], v[126:127]
	s_waitcnt lgkmcnt(4)
	v_pk_mul_f32 v[88:89], v[110:111], v[144:145]
	v_pk_fma_f32 v[2:3], v[108:109], v[124:125], v[2:3]
	v_pk_fma_f32 v[88:89], v[108:109], v[142:143], v[88:89]
	v_add_f32_e32 v90, v2, v3
	v_pk_mul_f32 v[2:3], v[114:115], v[126:127]
	v_add_f32_e32 v94, v88, v89
	v_pk_fma_f32 v[2:3], v[112:113], v[124:125], v[2:3]
	v_pk_mul_f32 v[88:89], v[114:115], v[144:145]
	s_lshl_b32 s0, s24, 3
	v_pk_fma_f32 v[96:97], v[112:113], v[142:143], v[88:89]
	v_add_f32_e32 v88, v2, v3
	v_pk_mul_f32 v[2:3], v[118:119], v[126:127]
	v_pk_mul_f32 v[126:127], v[122:123], v[126:127]
	v_add_f32_e32 v95, v96, v97
	v_pk_fma_f32 v[2:3], v[116:117], v[124:125], v[2:3]
	v_pk_mul_f32 v[96:97], v[118:119], v[144:145]
	v_pk_fma_f32 v[124:125], v[120:121], v[124:125], v[126:127]
	v_pk_mul_f32 v[126:127], v[122:123], v[144:145]
	v_mov_b32_e32 v0, s0
	v_pk_fma_f32 v[96:97], v[116:117], v[142:143], v[96:97]
	v_pk_fma_f32 v[126:127], v[120:121], v[142:143], v[126:127]
	ds_read_b64 v[92:93], v0 offset:28672
	v_add_f32_e32 v2, v2, v3
	v_add_f32_e32 v96, v96, v97
	v_add_f32_e32 v0, v124, v125
	v_add_f32_e32 v97, v126, v127
	v_add_f32_dpp v90, v90, v90 row_ror:8 row_mask:0xf bank_mask:0xf
	v_add_f32_dpp v88, v88, v88 row_ror:8 row_mask:0xf bank_mask:0xf
	v_add_f32_dpp v2, v2, v2 row_ror:8 row_mask:0xf bank_mask:0xf
	v_add_f32_dpp v0, v0, v0 row_ror:8 row_mask:0xf bank_mask:0xf
	v_add_f32_dpp v94, v94, v94 row_ror:8 row_mask:0xf bank_mask:0xf
	v_add_f32_dpp v95, v95, v95 row_ror:8 row_mask:0xf bank_mask:0xf
	v_add_f32_dpp v96, v96, v96 row_ror:8 row_mask:0xf bank_mask:0xf
	v_add_f32_dpp v97, v97, v97 row_ror:8 row_mask:0xf bank_mask:0xf
	v_add_f32_dpp v90, v90, v90 row_ror:4 row_mask:0xf bank_mask:0xf
	v_add_f32_dpp v88, v88, v88 row_ror:4 row_mask:0xf bank_mask:0xf
	v_add_f32_dpp v2, v2, v2 row_ror:4 row_mask:0xf bank_mask:0xf
	v_add_f32_dpp v0, v0, v0 row_ror:4 row_mask:0xf bank_mask:0xf
	v_add_f32_dpp v94, v94, v94 row_ror:4 row_mask:0xf bank_mask:0xf
	v_add_f32_dpp v95, v95, v95 row_ror:4 row_mask:0xf bank_mask:0xf
	v_add_f32_dpp v96, v96, v96 row_ror:4 row_mask:0xf bank_mask:0xf
	v_add_f32_dpp v97, v97, v97 row_ror:4 row_mask:0xf bank_mask:0xf
	v_add_f32_dpp v90, v90, v90 row_ror:2 row_mask:0xf bank_mask:0xf
	v_add_f32_dpp v88, v88, v88 row_ror:2 row_mask:0xf bank_mask:0xf
	v_add_f32_dpp v2, v2, v2 row_ror:2 row_mask:0xf bank_mask:0xf
	v_add_f32_dpp v0, v0, v0 row_ror:2 row_mask:0xf bank_mask:0xf
	v_add_f32_dpp v94, v94, v94 row_ror:2 row_mask:0xf bank_mask:0xf
	v_add_f32_dpp v95, v95, v95 row_ror:2 row_mask:0xf bank_mask:0xf
	v_add_f32_dpp v96, v96, v96 row_ror:2 row_mask:0xf bank_mask:0xf
	v_add_f32_dpp v97, v97, v97 row_ror:2 row_mask:0xf bank_mask:0xf
	v_add_f32_dpp v90, v90, v90 row_ror:1 row_mask:0xf bank_mask:0xf
	v_add_f32_dpp v88, v88, v88 row_ror:1 row_mask:0xf bank_mask:0xf
	v_add_f32_dpp v2, v2, v2 row_ror:1 row_mask:0xf bank_mask:0xf
	v_add_f32_dpp v0, v0, v0 row_ror:1 row_mask:0xf bank_mask:0xf
	v_add_f32_dpp v94, v94, v94 row_ror:1 row_mask:0xf bank_mask:0xf
	v_add_f32_dpp v95, v95, v95 row_ror:1 row_mask:0xf bank_mask:0xf
	v_add_f32_dpp v96, v96, v96 row_ror:1 row_mask:0xf bank_mask:0xf
	v_add_f32_dpp v97, v97, v97 row_ror:1 row_mask:0xf bank_mask:0xf
	s_and_saveexec_b64 s[0:1], s[44:45]
	s_cbranch_execz .LBB0_252
	v_mov_b32_e32 v3, v0
	v_mov_b32_e32 v91, v88
	s_waitcnt lgkmcnt(0)
	v_pk_fma_f32 v[96:97], v[92:93], v[2:3], v[96:97] op_sel_hi:[0,1,1]
	v_pk_fma_f32 v[94:95], v[92:93], v[90:91], v[94:95] op_sel_hi:[0,1,1]
	s_add_i32 s24, s24, s28
	v_pk_fma_f32 v[96:97], v[86:87], v[92:93], v[96:97] op_sel:[0,1,0]
	v_pk_fma_f32 v[92:93], v[84:85], v[92:93], v[94:95] op_sel:[0,1,0]
	s_lshl_b32 s24, s24, 10
	v_cvt_pk_bf16_f32 v92, v92, v93
	v_cvt_pk_bf16_f32 v93, v96, v97
	v_lshl_add_u64 v[94:95], v[100:101], 0, s[24:25]
	global_store_dwordx2 v[94:95], v[92:93], off
	s_branch .LBB0_252

; __device__ __forceinline__ int tid_() { int x = threadIdx.x; asm volatile("" : "+v"(x)); return x; }
; __device__ __forceinline__ int bid_() { int x = blockIdx.x; asm volatile("" : "+s"(x)); return x; }
; __device__ __forceinline__ void gemm_stage(const bf16_t* __restrict__ A, long lda, const bf16_t* __restrict__ Bt, long ldb, int kt, char* buf, int tid) {
; #pragma unroll
;     for (int i = 0; i < 4; ++i) {
;         const int b = tid * 16 + i * 4096, r = b >> 7, c = ((b & 127) >> 4) ^ (r & 7);
;         __builtin_amdgcn_global_load_lds((const unsigned*)(A + (long)r * lda + kt * 64 + c * 8), (__attribute__((address_space(3))) unsigned*)(buf + b), 16, 0, 0);
;         __builtin_amdgcn_global_load_lds((const unsigned*)(Bt + (long)r * ldb + kt * 64 + c * 8), (__attribute__((address_space(3))) unsigned*)(buf + 16384 + b), 16, 0, 0);
;     }
; }
; __device__ __forceinline__ void gemm_acc(const bf16_t* __restrict__ A, long lda, const bf16_t* __restrict__ Bt, long ldb, int K, f32x4 (&acc)[4][4], char* lds) {
;     const int tid = tid_(), wid = tid >> 6, lane = tid & 63, wr = wid >> 1, wc = wid & 1, fr = lane & 15, fq = lane >> 4;
;     const int nk = K >> 6;
;     gemm_stage(A, lda, Bt, ldb, 0, lds, tid);
;     asm volatile("s_waitcnt vmcnt(0)" ::: "memory");
;     __syncthreads();
; __device__ void ph_gemm_out(const Params& P, int l, char* lds) {
;     ...
;     for (int item = bid_(); item < 256 * 8; item += gridDim.x) {
;         const int mt = item / 8, nt = item % 8;
;         f32x4 acc[4][4]; zero_acc(acc);
;         gemm_acc(A + (size_t)mt * 128 * DM, DM, Wt + (size_t)nt * 128 * DM, DM, DM, acc, lds);
.LBB0_303:
	v_readlane_b32 s1, v239, 10
	s_mov_b32 s44, s21
	s_cmp_lg_u32 s1, 0x200
	s_cbranch_scc1 .Lmy_out_noperm
	s_and_b32 s44, s21, 7
	s_lshl_b32 s44, s44, 6
	s_bfe_u32 s1, s21, 0x60003
	s_or_b32 s44, s44, s1
	s_andn2_b32 s1, s21, 0x1ff
	s_or_b32 s44, s44, s1
.Lmy_out_noperm:
	s_lshr_b32 s0, s44, 3
	s_and_b32 s44, s44, 7
	s_ashr_i32 s1, s0, 31
	s_lshl_b64 s[48:49], s[0:1], 18
	v_readlane_b32 s1, v241, 41
	s_waitcnt vmcnt(9)
	v_mov_b32_e32 v20, v178
	s_add_u32 s26, s1, s48
	v_readlane_b32 s1, v241, 42
	s_addc_u32 s27, s1, s49
	v_ashrrev_i32_e32 v2, 3, v20
	s_ashr_i32 s45, s44, 31
	v_lshlrev_b32_e32 v82, 4, v20
	v_xor_b32_e32 v0, v2, v20
	v_ashrrev_i32_e32 v3, 31, v2
	s_lshl_b64 s[28:29], s[44:45], 18
	v_readlane_b32 s50, v241, 43
	v_lshlrev_b64 v[4:5], 11, v[2:3]
	v_lshlrev_b32_e32 v0, 4, v0
	v_add_u32_e32 v3, 0, v82
	v_readlane_b32 s51, v241, 44
	s_add_u32 s50, s50, s28
	v_lshl_add_u64 v[6:7], s[26:27], 0, v[4:5]
	v_and_b32_e32 v0, 0x70, v0
	v_readfirstlane_b32 s1, v3
	s_addc_u32 s51, s51, s29
	v_lshl_add_u64 v[6:7], v[6:7], 0, v[0:1]
	s_mov_b32 m0, s1
	v_lshrrev_b32_e32 v21, 4, v20
	global_load_lds_dwordx4 v[6:7], off
	v_lshl_add_u64 v[6:7], s[50:51], 0, v[4:5]
	v_lshl_add_u64 v[6:7], v[6:7], 0, v[0:1]
	v_add_u32_e32 v0, 0x4000, v3
	s_waitcnt vmcnt(0)
	v_bfe_u32 v22, v20, 4, 2
	v_readfirstlane_b32 s1, v0
	s_mov_b32 m0, s1
	v_add_u32_e32 v0, 0x1000, v82
	global_load_lds_dwordx4 v[6:7], off
	v_ashrrev_i32_e32 v6, 7, v0
	v_xor_b32_e32 v0, v6, v20
	v_ashrrev_i32_e32 v7, 31, v6
	v_lshlrev_b64 v[8:9], 11, v[6:7]
	v_lshlrev_b32_e32 v0, 4, v0
	v_add_u32_e32 v7, 0x1000, v3
	v_lshl_add_u64 v[10:11], s[26:27], 0, v[8:9]
	v_and_b32_e32 v0, 0x70, v0
	v_readfirstlane_b32 s1, v7
	v_lshl_add_u64 v[10:11], v[10:11], 0, v[0:1]
	s_mov_b32 m0, s1
	v_add_u32_e32 v7, 0x2000, v3
	global_load_lds_dwordx4 v[10:11], off
	v_lshl_add_u64 v[10:11], s[50:51], 0, v[8:9]
	v_lshl_add_u64 v[10:11], v[10:11], 0, v[0:1]
	v_add_u32_e32 v0, 0x5000, v3
	v_bitop3_b32 v2, v2, 7, v20 bitop3:0x48
	v_readfirstlane_b32 s1, v0
	s_mov_b32 m0, s1
	v_add_u32_e32 v0, 0x2000, v82
	global_load_lds_dwordx4 v[10:11], off
	v_ashrrev_i32_e32 v10, 7, v0
	v_xor_b32_e32 v0, v10, v20
	v_ashrrev_i32_e32 v11, 31, v10
	v_lshlrev_b64 v[12:13], 11, v[10:11]
	v_lshlrev_b32_e32 v0, 4, v0
	v_lshl_add_u64 v[14:15], s[26:27], 0, v[12:13]
	v_and_b32_e32 v0, 0x70, v0
	v_readfirstlane_b32 s1, v7
	v_lshl_add_u64 v[14:15], v[14:15], 0, v[0:1]
	s_mov_b32 m0, s1
	v_add_u32_e32 v7, 0x3000, v3
	global_load_lds_dwordx4 v[14:15], off
	v_lshl_add_u64 v[14:15], s[50:51], 0, v[12:13]
	v_lshl_add_u64 v[14:15], v[14:15], 0, v[0:1]
	v_add_u32_e32 v0, 0x6000, v3
	v_bitop3_b32 v6, v6, 7, v20 bitop3:0x48
	v_readfirstlane_b32 s1, v0
	s_mov_b32 m0, s1
	v_add_u32_e32 v0, 0x3000, v82
	global_load_lds_dwordx4 v[14:15], off
	v_ashrrev_i32_e32 v14, 7, v0
	v_xor_b32_e32 v0, v14, v20
	v_ashrrev_i32_e32 v15, 31, v14
	v_lshlrev_b64 v[16:17], 11, v[14:15]
	v_lshlrev_b32_e32 v0, 4, v0
	v_lshl_add_u64 v[18:19], s[26:27], 0, v[16:17]
	v_and_b32_e32 v0, 0x70, v0
	v_readfirstlane_b32 s1, v7
	v_lshl_add_u64 v[18:19], v[18:19], 0, v[0:1]
	s_mov_b32 m0, s1
	v_lshlrev_b32_e32 v6, 4, v6
	global_load_lds_dwordx4 v[18:19], off
	v_lshl_add_u64 v[18:19], s[50:51], 0, v[16:17]
	v_lshl_add_u64 v[18:19], v[18:19], 0, v[0:1]
	v_add_u32_e32 v0, 0x7000, v3
	v_lshrrev_b32_e32 v3, 1, v20
	v_readfirstlane_b32 s1, v0
	s_mov_b32 m0, s1
	v_and_b32_e32 v0, 15, v20
	global_load_lds_dwordx4 v[18:19], off
	v_and_or_b32 v0, v3, s46, v0
	v_and_b32_e32 v3, 7, v20
	v_bitop3_b32 v7, v21, v3, 3 bitop3:0x6c
	v_bitop3_b32 v3, v22, v3, 4 bitop3:0x36
	v_lshlrev_b32_e32 v85, 4, v7
	v_lshlrev_b32_e32 v84, 4, v3
	v_lshlrev_b32_e32 v7, 4, v2
	v_lshl_add_u64 v[2:3], s[48:49], 0, v[8:9]
	v_or_b32_e32 v2, v2, v6
	v_bitop3_b32 v10, v10, 7, v20 bitop3:0x48
	v_lshl_add_u64 v[68:69], s[40:41], 0, v[2:3]
	v_lshl_add_u64 v[2:3], s[48:49], 0, v[12:13]
	v_lshlrev_b32_e32 v10, 4, v10
	v_or_b32_e32 v2, v2, v10
	v_bitop3_b32 v11, v14, 7, v20 bitop3:0x48
	v_lshl_add_u64 v[70:71], s[40:41], 0, v[2:3]
	v_lshl_add_u64 v[2:3], s[48:49], 0, v[16:17]
	v_lshlrev_b32_e32 v11, 4, v11
	v_or_b32_e32 v2, v2, v11
	v_lshl_add_u64 v[72:73], s[40:41], 0, v[2:3]
	v_lshl_add_u64 v[2:3], s[28:29], 0, v[4:5]
	v_or_b32_e32 v2, v2, v7
	v_lshl_add_u64 v[74:75], s[42:43], 0, v[2:3]
	v_lshl_add_u64 v[2:3], s[28:29], 0, v[8:9]
	v_or_b32_e32 v2, v2, v6
	v_lshl_add_u64 v[76:77], s[42:43], 0, v[2:3]
	v_lshl_add_u64 v[2:3], s[28:29], 0, v[12:13]
	v_or_b32_e32 v2, v2, v10
	v_lshl_add_u64 v[78:79], s[42:43], 0, v[2:3]
	v_lshl_add_u64 v[2:3], s[28:29], 0, v[16:17]
	s_waitcnt vmcnt(0)
	v_lshl_add_u64 v[18:19], s[48:49], 0, v[4:5]
	v_or_b32_e32 v2, v2, v11
	v_lshlrev_b32_e32 v83, 7, v0
	v_lshlrev_b32_e32 v0, 7, v20
	v_or_b32_e32 v18, v18, v7
	v_lshl_add_u64 v[80:81], s[42:43], 0, v[2:3]
	v_mov_b32_e32 v2, 0
	v_and_b32_e32 v0, 0x2780, v0
	v_lshl_add_u64 v[66:67], s[40:41], 0, v[18:19]
	s_mov_b64 s[28:29], 0
	s_mov_b32 s1, 0x8000
	v_mov_b32_e32 v3, v2
	v_mov_b32_e32 v4, v2
	v_mov_b32_e32 v5, v2
	v_mov_b32_e32 v6, v2
	v_mov_b32_e32 v7, v2
	v_mov_b32_e32 v8, v2
	v_mov_b32_e32 v9, v2
	v_mov_b32_e32 v10, v2
	v_mov_b32_e32 v11, v2
	v_mov_b32_e32 v12, v2
	v_mov_b32_e32 v13, v2
	v_mov_b32_e32 v14, v2
	v_mov_b32_e32 v15, v2
	v_mov_b32_e32 v16, v2
	v_mov_b32_e32 v17, v2
	v_mov_b32_e32 v18, v2
	v_mov_b32_e32 v19, v2
	v_mov_b32_e32 v20, v2
	v_mov_b32_e32 v21, v2
	v_mov_b32_e32 v22, v2
	v_mov_b32_e32 v23, v2
	v_mov_b32_e32 v24, v2
	v_mov_b32_e32 v25, v2
	v_mov_b32_e32 v26, v2
	v_mov_b32_e32 v27, v2
	v_mov_b32_e32 v28, v2
	v_mov_b32_e32 v29, v2
	v_mov_b32_e32 v30, v2
	v_mov_b32_e32 v31, v2
	v_mov_b32_e32 v32, v2
	v_mov_b32_e32 v33, v2
	v_mov_b32_e32 v34, v2
	v_mov_b32_e32 v35, v2
	v_mov_b32_e32 v36, v2
	v_mov_b32_e32 v37, v2
	v_mov_b32_e32 v38, v2
	v_mov_b32_e32 v39, v2
	v_mov_b32_e32 v40, v2
	v_mov_b32_e32 v41, v2
	v_mov_b32_e32 v42, v2
	v_mov_b32_e32 v43, v2
	v_mov_b32_e32 v44, v2
	v_mov_b32_e32 v45, v2
	v_mov_b32_e32 v46, v2
	v_mov_b32_e32 v47, v2
	v_mov_b32_e32 v48, v2
	v_mov_b32_e32 v49, v2
	v_mov_b32_e32 v50, v2
	v_mov_b32_e32 v51, v2
	v_mov_b32_e32 v52, v2
	v_mov_b32_e32 v53, v2
	v_mov_b32_e32 v54, v2
	v_mov_b32_e32 v55, v2
	v_mov_b32_e32 v56, v2
	v_mov_b32_e32 v57, v2
	v_mov_b32_e32 v58, v2
	v_mov_b32_e32 v59, v2
	v_mov_b32_e32 v60, v2
	v_mov_b32_e32 v61, v2
	v_mov_b32_e32 v62, v2
	v_mov_b32_e32 v63, v2
	v_mov_b32_e32 v64, v2
	v_mov_b32_e32 v65, v2
	s_waitcnt lgkmcnt(0)
; __device__ __forceinline__ f32x4 mfma16(bf16x8 a, bf16x8 b, f32x4 c) { return __builtin_amdgcn_mfma_f32_16x16x32_bf16(a, b, c, 0, 0, 0); }
; __device__ __forceinline__ void gemm_acc(const bf16_t* __restrict__ A, long lda, const bf16_t* __restrict__ Bt, long ldb, int K, f32x4 (&acc)[4][4], char* lds) {
;     ...
;     for (int kt = 0; kt < nk; ++kt) {
;         char* cur = lds + (kt & 1) * 32768;
;         if (kt + 1 < nk) gemm_stage(A, lda, Bt, ldb, kt + 1, lds + ((kt + 1) & 1) * 32768, tid);
; #pragma unroll
;         for (int ks = 0; ks < 2; ++ks) {
;             bf16x8 af[4], bfr[4];
; #pragma unroll
;             for (int m = 0; m < 4; ++m) { const int row = wr * 64 + m * 16 + fr; af[m] = *reinterpret_cast<const bf16x8*>(cur + row * 128 + (((ks * 4 + fq) ^ (row & 7)) << 4)); }
; #pragma unroll
;             for (int n = 0; n < 4; ++n) { const int row = wc * 64 + n * 16 + fr; bfr[n] = *reinterpret_cast<const bf16x8*>(cur + 16384 + row * 128 + (((ks * 4 + fq) ^ (row & 7)) << 4)); }
;             __builtin_amdgcn_s_setprio(1);
; #pragma unroll
;             for (int m = 0; m < 4; ++m)
; #pragma unroll
;                 for (int n = 0; n < 4; ++n) acc[m][n] = mfma16(bfr[n], af[m], acc[m][n]);
;             __builtin_amdgcn_s_setprio(0);
;         }
;         asm volatile("s_waitcnt vmcnt(0)" ::: "memory");
;         __syncthreads();
;     }
	v_readfirstlane_b32 s27, v82
	s_mov_b64 s[28:29], 0
	s_add_i32 m0, s27, 0x8000
	s_nop 0
	global_load_lds_dwordx4 v[66:67], off
	s_add_i32 m0, s27, 0xc000
	s_nop 0
	global_load_lds_dwordx4 v[74:75], off
	s_add_i32 m0, s27, 0x9000
	s_nop 0
	global_load_lds_dwordx4 v[68:69], off
	s_add_i32 m0, s27, 0xd000
	s_nop 0
	global_load_lds_dwordx4 v[76:77], off
	s_add_i32 m0, s27, 0xa000
	s_nop 0
	global_load_lds_dwordx4 v[70:71], off
	s_add_i32 m0, s27, 0xe000
	s_nop 0
	global_load_lds_dwordx4 v[78:79], off
	s_add_i32 m0, s27, 0xb000
	s_nop 0
	global_load_lds_dwordx4 v[72:73], off
	s_add_i32 m0, s27, 0xf000
	s_nop 0
	global_load_lds_dwordx4 v[80:81], off
	s_movk_i32 s28, 0x80
	s_mov_b32 s1, 0
.Lmy_out_loop:
	s_waitcnt vmcnt(8)
	s_barrier
	s_and_b32 s26, s1, 1
	s_lshl_b32 s26, s26, 15
	v_add_u32_e32 v228, s26, v85
	v_add_u32_e32 v229, s26, v84
	v_add_u32_e32 v230, v228, v83
	v_add_u32_e32 v228, v228, v0
	v_add_u32_e32 v231, v229, v83
	v_add_u32_e32 v229, v229, v0
	ds_read_b128 v[86:89], v230
	ds_read_b128 v[90:93], v230 offset:2048
	ds_read_b128 v[94:97], v230 offset:4096
	ds_read_b128 v[98:101], v230 offset:6144
	ds_read_b128 v[190:193], v228 offset:16384
	ds_read_b128 v[194:197], v228 offset:18432
	ds_read_b128 v[198:201], v228 offset:20480
	ds_read_b128 v[202:205], v228 offset:22528
	ds_read_b128 v[162:165], v231
	ds_read_b128 v[166:169], v231 offset:2048
	ds_read_b128 v[170:173], v231 offset:4096
	ds_read_b128 v[174:177], v231 offset:6144
	ds_read_b128 v[206:209], v229 offset:16384
	ds_read_b128 v[210:213], v229 offset:18432
	ds_read_b128 v[214:217], v229 offset:20480
	ds_read_b128 v[222:225], v229 offset:22528
	s_waitcnt lgkmcnt(0)
	s_barrier
	s_cmp_ge_u32 s1, 14
	s_cbranch_scc1 .Lmy_out_nodma
	s_add_i32 s26, s26, s27
	s_setprio 1
	v_mfma_f32_16x16x32_bf16 v[62:65], v[190:193], v[86:89], v[62:65]
	v_mfma_f32_16x16x32_bf16 v[58:61], v[194:197], v[86:89], v[58:61]
	v_mfma_f32_16x16x32_bf16 v[54:57], v[198:201], v[86:89], v[54:57]
	v_mfma_f32_16x16x32_bf16 v[50:53], v[202:205], v[86:89], v[50:53]
	s_add_i32 m0, s26, 0x0
	v_lshl_add_u64 v[226:227], v[66:67], 0, s[28:29]
	global_load_lds_dwordx4 v[226:227], off
	v_mfma_f32_16x16x32_bf16 v[46:49], v[190:193], v[90:93], v[46:49]
	v_mfma_f32_16x16x32_bf16 v[42:45], v[194:197], v[90:93], v[42:45]
	v_mfma_f32_16x16x32_bf16 v[38:41], v[198:201], v[90:93], v[38:41]
	v_mfma_f32_16x16x32_bf16 v[34:37], v[202:205], v[90:93], v[34:37]
	s_add_i32 m0, s26, 0x4000
	v_lshl_add_u64 v[226:227], v[74:75], 0, s[28:29]
	global_load_lds_dwordx4 v[226:227], off
	v_mfma_f32_16x16x32_bf16 v[30:33], v[190:193], v[94:97], v[30:33]
	v_mfma_f32_16x16x32_bf16 v[26:29], v[194:197], v[94:97], v[26:29]
	v_mfma_f32_16x16x32_bf16 v[22:25], v[198:201], v[94:97], v[22:25]
	v_mfma_f32_16x16x32_bf16 v[18:21], v[202:205], v[94:97], v[18:21]
	s_add_i32 m0, s26, 0x1000
	v_lshl_add_u64 v[226:227], v[68:69], 0, s[28:29]
	global_load_lds_dwordx4 v[226:227], off
	v_mfma_f32_16x16x32_bf16 v[14:17], v[190:193], v[98:101], v[14:17]
	v_mfma_f32_16x16x32_bf16 v[10:13], v[194:197], v[98:101], v[10:13]
	v_mfma_f32_16x16x32_bf16 v[6:9], v[198:201], v[98:101], v[6:9]
	v_mfma_f32_16x16x32_bf16 v[2:5], v[202:205], v[98:101], v[2:5]
	s_add_i32 m0, s26, 0x5000
	v_lshl_add_u64 v[226:227], v[76:77], 0, s[28:29]
	global_load_lds_dwordx4 v[226:227], off
	v_mfma_f32_16x16x32_bf16 v[62:65], v[206:209], v[162:165], v[62:65]
	v_mfma_f32_16x16x32_bf16 v[58:61], v[210:213], v[162:165], v[58:61]
	v_mfma_f32_16x16x32_bf16 v[54:57], v[214:217], v[162:165], v[54:57]
	v_mfma_f32_16x16x32_bf16 v[50:53], v[222:225], v[162:165], v[50:53]
	s_add_i32 m0, s26, 0x2000
	v_lshl_add_u64 v[226:227], v[70:71], 0, s[28:29]
	global_load_lds_dwordx4 v[226:227], off
	v_mfma_f32_16x16x32_bf16 v[46:49], v[206:209], v[166:169], v[46:49]
	v_mfma_f32_16x16x32_bf16 v[42:45], v[210:213], v[166:169], v[42:45]
	v_mfma_f32_16x16x32_bf16 v[38:41], v[214:217], v[166:169], v[38:41]
	v_mfma_f32_16x16x32_bf16 v[34:37], v[222:225], v[166:169], v[34:37]
	s_add_i32 m0, s26, 0x6000
	v_lshl_add_u64 v[226:227], v[78:79], 0, s[28:29]
	global_load_lds_dwordx4 v[226:227], off
	v_mfma_f32_16x16x32_bf16 v[30:33], v[206:209], v[170:173], v[30:33]
	v_mfma_f32_16x16x32_bf16 v[26:29], v[210:213], v[170:173], v[26:29]
	v_mfma_f32_16x16x32_bf16 v[22:25], v[214:217], v[170:173], v[22:25]
	v_mfma_f32_16x16x32_bf16 v[18:21], v[222:225], v[170:173], v[18:21]
	s_add_i32 m0, s26, 0x3000
	v_lshl_add_u64 v[226:227], v[72:73], 0, s[28:29]
	global_load_lds_dwordx4 v[226:227], off
	v_mfma_f32_16x16x32_bf16 v[14:17], v[206:209], v[174:177], v[14:17]
	v_mfma_f32_16x16x32_bf16 v[10:13], v[210:213], v[174:177], v[10:13]
	v_mfma_f32_16x16x32_bf16 v[6:9], v[214:217], v[174:177], v[6:9]
	v_mfma_f32_16x16x32_bf16 v[2:5], v[222:225], v[174:177], v[2:5]
	s_add_i32 m0, s26, 0x7000
	v_lshl_add_u64 v[226:227], v[80:81], 0, s[28:29]
	global_load_lds_dwordx4 v[226:227], off
	s_setprio 0
	s_add_u32 s28, s28, 0x80
	s_addc_u32 s29, s29, 0
	s_branch .Lmy_out_join
; __device__ __forceinline__ f32x4 mfma16(bf16x8 a, bf16x8 b, f32x4 c) { return __builtin_amdgcn_mfma_f32_16x16x32_bf16(a, b, c, 0, 0, 0); }
; __device__ __forceinline__ void gemm_acc(const bf16_t* __restrict__ A, long lda, const bf16_t* __restrict__ Bt, long ldb, int K, f32x4 (&acc)[4][4], char* lds) {
;     ...
;     for (int kt = 0; kt < nk; ++kt) {
;         char* cur = lds + (kt & 1) * 32768;
;         if (kt + 1 < nk) gemm_stage(A, lda, Bt, ldb, kt + 1, lds + ((kt + 1) & 1) * 32768, tid);
; #pragma unroll
;         for (int ks = 0; ks < 2; ++ks) {
;             bf16x8 af[4], bfr[4];
; #pragma unroll
;             for (int m = 0; m < 4; ++m) { const int row = wr * 64 + m * 16 + fr; af[m] = *reinterpret_cast<const bf16x8*>(cur + row * 128 + (((ks * 4 + fq) ^ (row & 7)) << 4)); }
; #pragma unroll
;             for (int n = 0; n < 4; ++n) { const int row = wc * 64 + n * 16 + fr; bfr[n] = *reinterpret_cast<const bf16x8*>(cur + 16384 + row * 128 + (((ks * 4 + fq) ^ (row & 7)) << 4)); }
;             __builtin_amdgcn_s_setprio(1);
; #pragma unroll
;             for (int m = 0; m < 4; ++m)
; #pragma unroll
;                 for (int n = 0; n < 4; ++n) acc[m][n] = mfma16(bfr[n], af[m], acc[m][n]);
;             __builtin_amdgcn_s_setprio(0);
;         }
;         asm volatile("s_waitcnt vmcnt(0)" ::: "memory");
;         __syncthreads();
;     }
.Lmy_out_nodma:
	s_setprio 1
	v_mfma_f32_16x16x32_bf16 v[62:65], v[190:193], v[86:89], v[62:65]
	v_mfma_f32_16x16x32_bf16 v[58:61], v[194:197], v[86:89], v[58:61]
	v_mfma_f32_16x16x32_bf16 v[54:57], v[198:201], v[86:89], v[54:57]
	v_mfma_f32_16x16x32_bf16 v[50:53], v[202:205], v[86:89], v[50:53]
	v_mfma_f32_16x16x32_bf16 v[46:49], v[190:193], v[90:93], v[46:49]
	v_mfma_f32_16x16x32_bf16 v[42:45], v[194:197], v[90:93], v[42:45]
	v_mfma_f32_16x16x32_bf16 v[38:41], v[198:201], v[90:93], v[38:41]
	v_mfma_f32_16x16x32_bf16 v[34:37], v[202:205], v[90:93], v[34:37]
	v_mfma_f32_16x16x32_bf16 v[30:33], v[190:193], v[94:97], v[30:33]
	v_mfma_f32_16x16x32_bf16 v[26:29], v[194:197], v[94:97], v[26:29]
	v_mfma_f32_16x16x32_bf16 v[22:25], v[198:201], v[94:97], v[22:25]
	v_mfma_f32_16x16x32_bf16 v[18:21], v[202:205], v[94:97], v[18:21]
	v_mfma_f32_16x16x32_bf16 v[14:17], v[190:193], v[98:101], v[14:17]
	v_mfma_f32_16x16x32_bf16 v[10:13], v[194:197], v[98:101], v[10:13]
	v_mfma_f32_16x16x32_bf16 v[6:9], v[198:201], v[98:101], v[6:9]
	v_mfma_f32_16x16x32_bf16 v[2:5], v[202:205], v[98:101], v[2:5]
	v_mfma_f32_16x16x32_bf16 v[62:65], v[206:209], v[162:165], v[62:65]
	v_mfma_f32_16x16x32_bf16 v[58:61], v[210:213], v[162:165], v[58:61]
	v_mfma_f32_16x16x32_bf16 v[54:57], v[214:217], v[162:165], v[54:57]
	v_mfma_f32_16x16x32_bf16 v[50:53], v[222:225], v[162:165], v[50:53]
	v_mfma_f32_16x16x32_bf16 v[46:49], v[206:209], v[166:169], v[46:49]
	v_mfma_f32_16x16x32_bf16 v[42:45], v[210:213], v[166:169], v[42:45]
	v_mfma_f32_16x16x32_bf16 v[38:41], v[214:217], v[166:169], v[38:41]
	v_mfma_f32_16x16x32_bf16 v[34:37], v[222:225], v[166:169], v[34:37]
	v_mfma_f32_16x16x32_bf16 v[30:33], v[206:209], v[170:173], v[30:33]
	v_mfma_f32_16x16x32_bf16 v[26:29], v[210:213], v[170:173], v[26:29]
	v_mfma_f32_16x16x32_bf16 v[22:25], v[214:217], v[170:173], v[22:25]
	v_mfma_f32_16x16x32_bf16 v[18:21], v[222:225], v[170:173], v[18:21]
	v_mfma_f32_16x16x32_bf16 v[14:17], v[206:209], v[174:177], v[14:17]
	v_mfma_f32_16x16x32_bf16 v[10:13], v[210:213], v[174:177], v[10:13]
	v_mfma_f32_16x16x32_bf16 v[6:9], v[214:217], v[174:177], v[6:9]
	v_mfma_f32_16x16x32_bf16 v[2:5], v[222:225], v[174:177], v[2:5]
	s_setprio 0
.Lmy_out_join:
	s_add_i32 s1, s1, 1
	s_cmp_lt_u32 s1, 15
	s_cbranch_scc1 .Lmy_out_loop
	s_waitcnt vmcnt(0)
	s_barrier
	s_mov_b32 s45, 0x8000
	v_add_u32_e32 v82, s45, v85
	v_add_u32_e32 v78, v82, v83
	v_add_u32_e32 v82, v82, v0
	ds_read_b128 v[66:69], v78
	ds_read_b128 v[70:73], v78 offset:2048
	ds_read_b128 v[74:77], v78 offset:4096
	ds_read_b128 v[78:81], v78 offset:6144
	ds_read_b128 v[86:89], v82 offset:16384
	ds_read_b128 v[90:93], v82 offset:18432
	ds_read_b128 v[94:97], v82 offset:20480
	ds_read_b128 v[98:101], v82 offset:22528
	s_setprio 1
	s_waitcnt lgkmcnt(3)
	v_mfma_f32_16x16x32_bf16 v[62:65], v[86:89], v[66:69], v[62:65]
	s_waitcnt lgkmcnt(2)
	v_mfma_f32_16x16x32_bf16 v[58:61], v[90:93], v[66:69], v[58:61]
	s_waitcnt lgkmcnt(1)
	v_mfma_f32_16x16x32_bf16 v[54:57], v[94:97], v[66:69], v[54:57]
	s_waitcnt lgkmcnt(0)
	v_mfma_f32_16x16x32_bf16 v[50:53], v[98:101], v[66:69], v[50:53]
	v_mfma_f32_16x16x32_bf16 v[46:49], v[86:89], v[70:73], v[46:49]
	v_mfma_f32_16x16x32_bf16 v[42:45], v[90:93], v[70:73], v[42:45]
	v_mfma_f32_16x16x32_bf16 v[38:41], v[94:97], v[70:73], v[38:41]
	v_mfma_f32_16x16x32_bf16 v[34:37], v[98:101], v[70:73], v[34:37]
	v_mfma_f32_16x16x32_bf16 v[66:69], v[86:89], v[74:77], v[30:33]
	v_mfma_f32_16x16x32_bf16 v[70:73], v[90:93], v[74:77], v[26:29]
	v_mfma_f32_16x16x32_bf16 v[22:25], v[94:97], v[74:77], v[22:25]
	v_mfma_f32_16x16x32_bf16 v[18:21], v[98:101], v[74:77], v[18:21]
	v_mfma_f32_16x16x32_bf16 v[74:77], v[86:89], v[78:81], v[14:17]
	v_mfma_f32_16x16x32_bf16 v[86:89], v[90:93], v[78:81], v[10:13]
	v_mfma_f32_16x16x32_bf16 v[90:93], v[94:97], v[78:81], v[6:9]
	v_mfma_f32_16x16x32_bf16 v[2:5], v[98:101], v[78:81], v[2:5]
	s_setprio 0
	v_add_u32_e32 v14, s45, v84
	v_add_u32_e32 v15, v14, v83
	v_add_u32_e32 v0, v14, v0
	ds_read_b128 v[6:9], v15
	ds_read_b128 v[10:13], v15 offset:2048
	ds_read_b128 v[78:81], v15 offset:4096
	ds_read_b128 v[82:85], v15 offset:6144
	ds_read_b128 v[94:97], v0 offset:16384
	ds_read_b128 v[98:101], v0 offset:18432
	ds_read_b128 v[102:105], v0 offset:20480
	ds_read_b128 v[106:109], v0 offset:22528
	s_setprio 1
	s_waitcnt lgkmcnt(3)
	v_mfma_f32_16x16x32_bf16 v[62:65], v[94:97], v[6:9], v[62:65]
	s_waitcnt lgkmcnt(2)
	v_mfma_f32_16x16x32_bf16 v[58:61], v[98:101], v[6:9], v[58:61]
	s_waitcnt lgkmcnt(1)
	v_mfma_f32_16x16x32_bf16 v[30:33], v[102:105], v[6:9], v[54:57]
	s_waitcnt lgkmcnt(0)
	v_mfma_f32_16x16x32_bf16 v[14:17], v[106:109], v[6:9], v[50:53]
	v_mfma_f32_16x16x32_bf16 v[46:49], v[94:97], v[10:13], v[46:49]
	v_mfma_f32_16x16x32_bf16 v[50:53], v[98:101], v[10:13], v[42:45]
	v_mfma_f32_16x16x32_bf16 v[26:29], v[102:105], v[10:13], v[38:41]
	v_mfma_f32_16x16x32_bf16 v[10:13], v[106:109], v[10:13], v[34:37]
	v_mfma_f32_16x16x32_bf16 v[54:57], v[94:97], v[78:81], v[66:69]
	v_mfma_f32_16x16x32_bf16 v[66:69], v[98:101], v[78:81], v[70:73]
	v_mfma_f32_16x16x32_bf16 v[22:25], v[102:105], v[78:81], v[22:25]
	v_mfma_f32_16x16x32_bf16 v[6:9], v[106:109], v[78:81], v[18:21]
	v_mfma_f32_16x16x32_bf16 v[70:73], v[94:97], v[82:85], v[74:77]
	v_mfma_f32_16x16x32_bf16 v[74:77], v[98:101], v[82:85], v[86:89]
	v_mfma_f32_16x16x32_bf16 v[18:21], v[102:105], v[82:85], v[90:93]
	v_mfma_f32_16x16x32_bf16 v[2:5], v[106:109], v[82:85], v[2:5]
	s_setprio 0
	v_mov_b32_e32 v0, v178
	s_waitcnt vmcnt(0)
	s_barrier
; __device__ __forceinline__ int tid_() { int x = threadIdx.x; asm volatile("" : "+v"(x)); return x; }
; __device__ __forceinline__ void resid_tile(const f32x4 (&acc)[4][4], float* __restrict__ h, int row0, int col0, const float* __restrict__ gate) {
;     const int tid = tid_(), wid = tid >> 6, lane = tid & 63, wr = wid >> 1, wc = wid & 1, fr = lane & 15, fq = lane >> 4;
;     const int b = row0 >> 11;
; #pragma unroll
;     for (int n = 0; n < 4; ++n) {
;         const int col = col0 + wc * 64 + n * 16 + fq * 4;
;         const f32x4 gv = *(const f32x4*)(gate + (size_t)b * 6144 + col);
; #pragma unroll
;         for (int m = 0; m < 4; ++m) {
;             float* hp = h + (size_t)(row0 + wr * 64 + m * 16 + fr) * DM + col;
;             const f32x4 o = *(const f32x4*)hp + gv * acc[m][n];
;             *(f32x4*)hp = o;
;         }
;     }
; }
	s_lshl_b32 s1, s44, 7
	v_lshrrev_b32_e32 v35, 2, v0
	v_and_b32_e32 v34, 64, v0
	v_and_b32_e32 v35, 12, v35
	s_lshl_b32 s26, s0, 7
	s_ashr_i32 s0, s0, 4
	v_or3_b32 v34, v34, s1, v35
	v_ashrrev_i32_e32 v35, 1, v0
	s_mul_hi_i32 s1, s0, 0x6000
	s_mulk_i32 s0, 0x6000
	v_and_b32_e32 v35, 0xffffffc0, v35
	v_and_or_b32 v0, v0, 15, s26
	s_add_u32 s0, s24, s0
	v_add_u32_e32 v82, v0, v35
	v_ashrrev_i32_e32 v35, 31, v34
	v_readlane_b32 s48, v241, 13
	s_addc_u32 s1, s30, s1
	v_ashrrev_i32_e32 v83, 31, v82
	v_lshlrev_b64 v[34:35], 2, v[34:35]
	v_readlane_b32 s50, v241, 15
	v_readlane_b32 s51, v241, 16
	v_lshlrev_b64 v[38:39], 12, v[82:83]
	v_lshl_add_u64 v[36:37], s[0:1], 0, v[34:35]
	v_lshl_add_u64 v[34:35], s[50:51], 0, v[34:35]
	v_lshl_add_u64 v[38:39], v[34:35], 0, v[38:39]
	global_load_dwordx4 v[78:81], v[36:37], off
	global_load_dwordx4 v[40:43], v[38:39], off
	v_readlane_b32 s0, v239, 10
	s_add_i32 s21, s21, s0
	s_cmpk_gt_i32 s21, 0x7ff
	v_readlane_b32 s49, v241, 14
	v_readlane_b32 s1, v239, 11
	s_waitcnt vmcnt(0)
	v_pk_fma_f32 v[42:43], v[64:65], v[80:81], v[42:43]
	v_pk_fma_f32 v[40:41], v[62:63], v[78:79], v[40:41]
	global_store_dwordx4 v[38:39], v[40:43], off
	s_nop 1
	v_or_b32_e32 v40, 16, v82
	v_ashrrev_i32_e32 v41, 31, v40
	v_lshlrev_b64 v[40:41], 12, v[40:41]
	v_lshl_add_u64 v[40:41], v[34:35], 0, v[40:41]
	global_load_dwordx4 v[42:45], v[40:41], off
	s_waitcnt vmcnt(0)
	v_pk_fma_f32 v[44:45], v[48:49], v[80:81], v[44:45]
	v_pk_fma_f32 v[42:43], v[46:47], v[78:79], v[42:43]
	global_store_dwordx4 v[40:41], v[42:45], off
	s_nop 1
	v_or_b32_e32 v42, 32, v82
	v_ashrrev_i32_e32 v43, 31, v42
	v_lshlrev_b64 v[42:43], 12, v[42:43]
	v_lshl_add_u64 v[42:43], v[34:35], 0, v[42:43]
	global_load_dwordx4 v[44:47], v[42:43], off
	s_waitcnt vmcnt(0)
	v_pk_fma_f32 v[46:47], v[56:57], v[80:81], v[46:47]
	v_pk_fma_f32 v[44:45], v[54:55], v[78:79], v[44:45]
	global_store_dwordx4 v[42:43], v[44:47], off
	s_nop 1
	v_or_b32_e32 v44, 48, v82
	v_ashrrev_i32_e32 v45, 31, v44
	v_lshlrev_b64 v[44:45], 12, v[44:45]
	v_lshl_add_u64 v[34:35], v[34:35], 0, v[44:45]
	global_load_dwordx4 v[44:47], v[34:35], off
	s_waitcnt vmcnt(0)
	v_pk_fma_f32 v[46:47], v[72:73], v[80:81], v[46:47]
	v_pk_fma_f32 v[44:45], v[70:71], v[78:79], v[44:45]
	global_store_dwordx4 v[34:35], v[44:47], off
	global_load_dwordx4 v[44:47], v[36:37], off offset:64
	s_nop 0
	global_load_dwordx4 v[54:57], v[38:39], off offset:64
	s_waitcnt vmcnt(0)
	v_pk_fma_f32 v[56:57], v[60:61], v[46:47], v[56:57]
	v_pk_fma_f32 v[54:55], v[58:59], v[44:45], v[54:55]
	global_store_dwordx4 v[38:39], v[54:57], off offset:64
	global_load_dwordx4 v[54:57], v[40:41], off offset:64
	s_waitcnt vmcnt(0)
	v_pk_fma_f32 v[52:53], v[52:53], v[46:47], v[56:57]
	v_pk_fma_f32 v[50:51], v[50:51], v[44:45], v[54:55]
	global_store_dwordx4 v[40:41], v[50:53], off offset:64
	global_load_dwordx4 v[48:51], v[42:43], off offset:64
	s_waitcnt vmcnt(0)
	v_pk_fma_f32 v[48:49], v[66:67], v[44:45], v[48:49]
	v_pk_fma_f32 v[50:51], v[68:69], v[46:47], v[50:51]
	global_store_dwordx4 v[42:43], v[48:51], off offset:64
	global_load_dwordx4 v[48:51], v[34:35], off offset:64
	s_waitcnt vmcnt(0)
	v_pk_fma_f32 v[46:47], v[76:77], v[46:47], v[50:51]
	v_pk_fma_f32 v[44:45], v[74:75], v[44:45], v[48:49]
	global_store_dwordx4 v[34:35], v[44:47], off offset:64
	global_load_dwordx4 v[44:47], v[36:37], off offset:128
	s_nop 0
	global_load_dwordx4 v[48:51], v[38:39], off offset:128
	s_waitcnt vmcnt(0)
	v_pk_fma_f32 v[32:33], v[32:33], v[46:47], v[50:51]
	v_pk_fma_f32 v[30:31], v[30:31], v[44:45], v[48:49]
	global_store_dwordx4 v[38:39], v[30:33], off offset:128
	global_load_dwordx4 v[30:33], v[40:41], off offset:128
	s_waitcnt vmcnt(0)
	v_pk_fma_f32 v[28:29], v[28:29], v[46:47], v[32:33]
	v_pk_fma_f32 v[26:27], v[26:27], v[44:45], v[30:31]
	global_store_dwordx4 v[40:41], v[26:29], off offset:128
	global_load_dwordx4 v[26:29], v[42:43], off offset:128
	s_waitcnt vmcnt(0)
	v_pk_fma_f32 v[24:25], v[24:25], v[46:47], v[28:29]
	v_pk_fma_f32 v[22:23], v[22:23], v[44:45], v[26:27]
	global_store_dwordx4 v[42:43], v[22:25], off offset:128
	global_load_dwordx4 v[22:25], v[34:35], off offset:128
	s_waitcnt vmcnt(0)
	v_pk_fma_f32 v[20:21], v[20:21], v[46:47], v[24:25]
	v_pk_fma_f32 v[18:19], v[18:19], v[44:45], v[22:23]
	global_store_dwordx4 v[34:35], v[18:21], off offset:128
	global_load_dwordx4 v[18:21], v[36:37], off offset:192
	s_nop 0
	global_load_dwordx4 v[22:25], v[38:39], off offset:192
	s_waitcnt vmcnt(0)
	v_pk_fma_f32 v[16:17], v[16:17], v[20:21], v[24:25]
	v_pk_fma_f32 v[14:15], v[14:15], v[18:19], v[22:23]
	global_store_dwordx4 v[38:39], v[14:17], off offset:192
	global_load_dwordx4 v[14:17], v[40:41], off offset:192
	s_waitcnt vmcnt(0)
	v_pk_fma_f32 v[12:13], v[12:13], v[20:21], v[16:17]
	v_pk_fma_f32 v[10:11], v[10:11], v[18:19], v[14:15]
	global_store_dwordx4 v[40:41], v[10:13], off offset:192
	global_load_dwordx4 v[10:13], v[42:43], off offset:192
	s_waitcnt vmcnt(0)
	v_pk_fma_f32 v[8:9], v[8:9], v[20:21], v[12:13]
	v_pk_fma_f32 v[6:7], v[6:7], v[18:19], v[10:11]
	global_store_dwordx4 v[42:43], v[6:9], off offset:192
	global_load_dwordx4 v[6:9], v[34:35], off offset:192
	s_waitcnt vmcnt(0)
	v_pk_fma_f32 v[4:5], v[4:5], v[20:21], v[8:9]
	v_pk_fma_f32 v[2:3], v[2:3], v[18:19], v[6:7]
	global_store_dwordx4 v[34:35], v[2:5], off offset:192
	s_cbranch_scc0 .LBB0_303

; __device__ __forceinline__ int tid_() { int x = threadIdx.x; asm volatile("" : "+v"(x)); return x; }
; __device__ __forceinline__ int bid_() { int x = blockIdx.x; asm volatile("" : "+s"(x)); return x; }
; __device__ __forceinline__ void gemm_stage(const bf16_t* __restrict__ A, long lda, const bf16_t* __restrict__ Bt, long ldb, int kt, char* buf, int tid) {
; #pragma unroll
;     for (int i = 0; i < 4; ++i) {
;         const int b = tid * 16 + i * 4096, r = b >> 7, c = ((b & 127) >> 4) ^ (r & 7);
;         __builtin_amdgcn_global_load_lds((const unsigned*)(A + (long)r * lda + kt * 64 + c * 8), (__attribute__((address_space(3))) unsigned*)(buf + b), 16, 0, 0);
;         __builtin_amdgcn_global_load_lds((const unsigned*)(Bt + (long)r * ldb + kt * 64 + c * 8), (__attribute__((address_space(3))) unsigned*)(buf + 16384 + b), 16, 0, 0);
;     }
; }
; __device__ __forceinline__ void gemm_acc(const bf16_t* __restrict__ A, long lda, const bf16_t* __restrict__ Bt, long ldb, int K, f32x4 (&acc)[4][4], char* lds) {
;     const int tid = tid_(), wid = tid >> 6, lane = tid & 63, wr = wid >> 1, wc = wid & 1, fr = lane & 15, fq = lane >> 4;
;     const int nk = K >> 6;
;     gemm_stage(A, lda, Bt, ldb, 0, lds, tid);
;     asm volatile("s_waitcnt vmcnt(0)" ::: "memory");
;     __syncthreads();
; __device__ void ph_gemm_merge(const Params& P, char* lds) {
;     ...
;     for (int item = bid_(); item < 256 * 8; item += gridDim.x) {
;         const int mt = item / 8, nt = item % 8;
;         unsigned mpk[4][4][2];
; #pragma unroll
;         for (int m = 0; m < 4; ++m)
; #pragma unroll
;             for (int q = 0; q < 4; ++q) { mpk[m][q][0] = 0u; mpk[m][q][1] = 0u; }
; #pragma unroll 1
;         for (int n = 0; n < 4; ++n) {
;             unsigned gpk[4][4][2];
;             {
;                 f32x4 acc[4][4]; zero_acc(acc);
;                 gemm_acc(U + (size_t)mt * 128 * DM, DM, Wt + (size_t)(GATE_ROW0 + n * 1024 + nt * 128) * DM, DM, DM, acc, lds);
.LBB0_309:
	v_readlane_b32 s1, v239, 10
	s_mov_b32 s63, s21
	s_cmp_lg_u32 s1, 0x200
	s_cbranch_scc1 .Lmy_merge_noperm
	s_and_b32 s63, s21, 7
	s_lshl_b32 s63, s63, 6
	s_bfe_u32 s1, s21, 0x60003
	s_or_b32 s63, s63, s1
	s_andn2_b32 s1, s21, 0x1ff
	s_or_b32 s63, s63, s1
.Lmy_merge_noperm:
	s_ashr_i32 s26, s63, 3
	s_and_b32 s0, s63, 0x1fffff8
	s_ashr_i32 s27, s26, 31
	s_sub_i32 s24, s63, s0
	s_lshl_b64 s[0:1], s[26:27], 18
	v_readlane_b32 s28, v241, 35
	v_readlane_b32 s29, v241, 36
	s_add_u32 s48, s28, s0
	s_addc_u32 s49, s29, s1
	s_lshl_b32 s44, s24, 7
	s_add_i32 s30, s44, 0x1b80
	s_lshl_b64 s[28:29], s[26:27], 17
	s_ashr_i32 s45, s44, 31
	s_add_u32 s61, s74, s28
	s_addc_u32 s62, s75, s29
	v_readlane_b32 s24, v239, 57
	s_add_u32 s50, s24, s0
	v_readlane_b32 s24, v239, 58
	s_addc_u32 s51, s24, s1
	s_lshl_b32 s24, s63, 7
	s_lshl_b32 s26, s26, 10
	s_sub_i32 s24, s24, s26
	s_add_i32 s52, s24, 0x1b80
	v_readlane_b32 s24, v239, 59
	s_add_u32 s54, s24, s28
	v_readlane_b32 s24, v239, 60
	s_addc_u32 s55, s24, s29
	s_lshl_b64 s[26:27], s[44:45], 10
	v_readlane_b32 s24, v239, 61
	s_add_u32 s56, s24, s26
	v_readlane_b32 s24, v239, 62
	s_addc_u32 s57, s24, s27
	v_mov_b32_e32 v189, 0
	s_mov_b32 s63, 0
	v_mov_b32_e32 v160, 0
	v_mov_b32_e32 v161, 0
	v_mov_b32_e32 v158, 0
	v_mov_b32_e32 v159, 0
	v_mov_b32_e32 v156, 0
	v_mov_b32_e32 v157, 0
	v_mov_b32_e32 v154, 0
	v_mov_b32_e32 v155, 0
	v_mov_b32_e32 v152, 0
	v_mov_b32_e32 v153, 0
	v_mov_b32_e32 v150, 0
	v_mov_b32_e32 v151, 0
	v_mov_b32_e32 v148, 0
	v_mov_b32_e32 v149, 0
	v_mov_b32_e32 v146, 0
	v_mov_b32_e32 v147, 0
	v_mov_b32_e32 v144, 0
	v_mov_b32_e32 v145, 0
	v_mov_b32_e32 v142, 0
	v_mov_b32_e32 v143, 0
	v_mov_b32_e32 v140, 0
	v_mov_b32_e32 v141, 0
	v_mov_b32_e32 v138, 0
	v_mov_b32_e32 v139, 0
	v_mov_b32_e32 v136, 0
	v_mov_b32_e32 v137, 0
	v_mov_b32_e32 v134, 0
	v_mov_b32_e32 v135, 0
	v_mov_b32_e32 v132, 0
	v_mov_b32_e32 v133, 0
	v_mov_b32_e32 v130, 0
	v_mov_b32_e32 v131, 0
	s_mov_b32 s40, 0x1ffffc0
.LBB0_310:
	s_ashr_i32 s53, s52, 31
	s_lshl_b64 s[28:29], s[52:53], 11
	s_lshl_b32 s53, s63, 10
	s_waitcnt vmcnt(9)
	v_mov_b32_e32 v20, v178
	s_add_i32 s26, s30, s53
	s_ashr_i32 s27, s26, 31
	v_ashrrev_i32_e32 v2, 3, v20
	v_lshlrev_b32_e32 v82, 4, v20
	v_xor_b32_e32 v0, v2, v20
	v_ashrrev_i32_e32 v3, 31, v2
	s_lshl_b64 s[26:27], s[26:27], 11
	v_lshlrev_b64 v[4:5], 11, v[2:3]
	v_lshlrev_b32_e32 v0, 4, v0
	v_add_u32_e32 v3, 0, v82
	s_add_u32 s26, s74, s26
	v_lshl_add_u64 v[6:7], s[48:49], 0, v[4:5]
	v_and_b32_e32 v0, 0x70, v0
	v_readfirstlane_b32 s24, v3
	s_addc_u32 s27, s75, s27
	v_lshl_add_u64 v[6:7], v[6:7], 0, v[0:1]
	s_mov_b32 m0, s24
	v_bitop3_b32 v2, v2, 7, v20 bitop3:0x48
	global_load_lds_dwordx4 v[6:7], off
	v_lshl_add_u64 v[6:7], s[26:27], 0, v[4:5]
	v_lshl_add_u64 v[6:7], v[6:7], 0, v[0:1]
	v_add_u32_e32 v0, 0x4000, v3
	v_lshl_or_b32 v4, v2, 4, v4
	v_readfirstlane_b32 s24, v0
	s_mov_b32 m0, s24
	v_add_u32_e32 v0, 0x1000, v82
	global_load_lds_dwordx4 v[6:7], off
	v_ashrrev_i32_e32 v6, 7, v0
	v_xor_b32_e32 v0, v6, v20
	v_ashrrev_i32_e32 v7, 31, v6
	v_lshlrev_b64 v[8:9], 11, v[6:7]
	v_lshlrev_b32_e32 v0, 4, v0
	v_add_u32_e32 v7, 0x1000, v3
	v_lshl_add_u64 v[10:11], s[48:49], 0, v[8:9]
	v_and_b32_e32 v0, 0x70, v0
	v_readfirstlane_b32 s24, v7
	v_lshl_add_u64 v[10:11], v[10:11], 0, v[0:1]
	s_mov_b32 m0, s24
	v_add_u32_e32 v7, 0x2000, v3
	global_load_lds_dwordx4 v[10:11], off
	v_lshl_add_u64 v[10:11], s[26:27], 0, v[8:9]
	v_lshl_add_u64 v[10:11], v[10:11], 0, v[0:1]
	v_add_u32_e32 v0, 0x5000, v3
	v_bitop3_b32 v2, v6, 7, v20 bitop3:0x48
	v_readfirstlane_b32 s24, v0
	s_mov_b32 m0, s24
	v_add_u32_e32 v0, 0x2000, v82
	global_load_lds_dwordx4 v[10:11], off
	v_ashrrev_i32_e32 v10, 7, v0
	v_xor_b32_e32 v0, v10, v20
	v_ashrrev_i32_e32 v11, 31, v10
	v_lshlrev_b64 v[12:13], 11, v[10:11]
	v_lshlrev_b32_e32 v0, 4, v0
	v_lshl_add_u64 v[14:15], s[48:49], 0, v[12:13]
	v_and_b32_e32 v0, 0x70, v0
	v_readfirstlane_b32 s24, v7
	v_lshl_add_u64 v[14:15], v[14:15], 0, v[0:1]
	s_mov_b32 m0, s24
	v_add_u32_e32 v7, 0x3000, v3
	global_load_lds_dwordx4 v[14:15], off
	v_lshl_add_u64 v[14:15], s[26:27], 0, v[12:13]
	v_lshl_add_u64 v[14:15], v[14:15], 0, v[0:1]
	v_add_u32_e32 v0, 0x6000, v3
	v_lshl_or_b32 v8, v2, 4, v8
	v_readfirstlane_b32 s24, v0
	s_mov_b32 m0, s24
	v_add_u32_e32 v0, 0x3000, v82
	global_load_lds_dwordx4 v[14:15], off
	v_ashrrev_i32_e32 v14, 7, v0
	v_xor_b32_e32 v0, v14, v20
	v_ashrrev_i32_e32 v15, 31, v14
	v_lshlrev_b64 v[16:17], 11, v[14:15]
	v_lshlrev_b32_e32 v0, 4, v0
	v_lshl_add_u64 v[18:19], s[48:49], 0, v[16:17]
	v_and_b32_e32 v0, 0x70, v0
	v_readfirstlane_b32 s24, v7
	v_lshl_add_u64 v[18:19], v[18:19], 0, v[0:1]
	s_mov_b32 m0, s24
	v_bitop3_b32 v2, v10, 7, v20 bitop3:0x48
	global_load_lds_dwordx4 v[18:19], off
	v_lshl_add_u64 v[18:19], s[26:27], 0, v[16:17]
	v_lshl_add_u64 v[18:19], v[18:19], 0, v[0:1]
	v_add_u32_e32 v0, 0x7000, v3
	v_lshrrev_b32_e32 v3, 1, v20
	v_readfirstlane_b32 s24, v0
	s_mov_b32 m0, s24
	v_and_b32_e32 v0, 15, v20
	global_load_lds_dwordx4 v[18:19], off
	v_readlane_b32 s24, v239, 59
	v_lshrrev_b32_e32 v21, 4, v20
	s_waitcnt vmcnt(0)
	v_bfe_u32 v22, v20, 4, 2
	s_waitcnt vmcnt(0)
; __device__ __forceinline__ int tid_() { int x = threadIdx.x; asm volatile("" : "+v"(x)); return x; }
; __device__ __forceinline__ void gemm_acc(const bf16_t* __restrict__ A, long lda, const bf16_t* __restrict__ Bt, long ldb, int K, f32x4 (&acc)[4][4], char* lds) {
;     const int tid = tid_(), wid = tid >> 6, lane = tid & 63, wr = wid >> 1, wc = wid & 1, fr = lane & 15, fq = lane >> 4;
;     const int nk = K >> 6;
;     gemm_stage(A, lda, Bt, ldb, 0, lds, tid);
;     asm volatile("s_waitcnt vmcnt(0)" ::: "memory");
;     __syncthreads();
;     for (int kt = 0; kt < nk; ++kt) {
;         char* cur = lds + (kt & 1) * 32768;
;         if (kt + 1 < nk) gemm_stage(A, lda, Bt, ldb, kt + 1, lds + ((kt + 1) & 1) * 32768, tid);
; __device__ void ph_gemm_merge(const Params& P, char* lds) {
;     ...
;                 f32x4 acc[4][4]; zero_acc(acc);
;                 gemm_acc(U + (size_t)mt * 128 * DM, DM, Wt + (size_t)(GATE_ROW0 + n * 1024 + nt * 128) * DM, DM, DM, acc, lds);
	v_and_or_b32 v0, v3, s40, v0
	v_and_b32_e32 v3, 7, v20
	v_lshl_or_b32 v12, v2, 4, v12
	v_bitop3_b32 v2, v14, 7, v20 bitop3:0x48
	s_add_u32 s26, s24, s28
	v_readlane_b32 s24, v239, 60
	v_bitop3_b32 v7, v21, v3, 3 bitop3:0x6c
	v_lshlrev_b32_e32 v83, 7, v0
	v_lshlrev_b32_e32 v0, 7, v20
	v_bitop3_b32 v3, v22, v3, 4 bitop3:0x36
	v_lshl_or_b32 v16, v2, 4, v16
	s_addc_u32 s27, s24, s29
	v_lshlrev_b32_e32 v85, 4, v7
	v_and_b32_e32 v0, 0x2780, v0
	v_lshlrev_b32_e32 v84, 4, v3
	v_lshl_add_u64 v[66:67], s[50:51], 0, v[4:5]
	v_lshl_add_u64 v[68:69], s[50:51], 0, v[8:9]
	v_lshl_add_u64 v[70:71], s[50:51], 0, v[12:13]
	v_lshl_add_u64 v[72:73], s[50:51], 0, v[16:17]
	v_lshl_add_u64 v[74:75], s[26:27], 0, v[4:5]
	v_lshl_add_u64 v[76:77], s[26:27], 0, v[8:9]
	v_lshl_add_u64 v[78:79], s[26:27], 0, v[12:13]
	v_lshl_add_u64 v[80:81], s[26:27], 0, v[16:17]
	s_mov_b64 s[28:29], 0
	s_mov_b32 s24, 0x8000
	v_mov_b32_e32 v2, 0
	v_mov_b32_e32 v3, v189
	v_mov_b32_e32 v4, v189
	v_mov_b32_e32 v5, v189
	v_mov_b32_e32 v6, 0
	v_mov_b32_e32 v7, v189
	v_mov_b32_e32 v8, v189
	v_mov_b32_e32 v9, v189
	v_mov_b32_e32 v10, 0
	v_mov_b32_e32 v11, v189
	v_mov_b32_e32 v12, v189
	v_mov_b32_e32 v13, v189
	v_mov_b32_e32 v14, 0
	v_mov_b32_e32 v15, v189
	v_mov_b32_e32 v16, v189
	v_mov_b32_e32 v17, v189
	v_mov_b32_e32 v18, 0
	v_mov_b32_e32 v19, v189
	v_mov_b32_e32 v20, v189
	v_mov_b32_e32 v21, v189
	v_mov_b32_e32 v22, 0
	v_mov_b32_e32 v23, v189
	v_mov_b32_e32 v24, v189
	v_mov_b32_e32 v25, v189
	v_mov_b32_e32 v26, 0
	v_mov_b32_e32 v27, v189
	v_mov_b32_e32 v28, v189
	v_mov_b32_e32 v29, v189
	v_mov_b32_e32 v30, 0
	v_mov_b32_e32 v31, v189
	v_mov_b32_e32 v32, v189
	v_mov_b32_e32 v33, v189
	v_mov_b32_e32 v34, 0
	v_mov_b32_e32 v35, v189
	v_mov_b32_e32 v36, v189
	v_mov_b32_e32 v37, v189
	v_mov_b32_e32 v38, 0
	v_mov_b32_e32 v39, v189
	v_mov_b32_e32 v40, v189
	v_mov_b32_e32 v41, v189
	v_mov_b32_e32 v42, 0
	v_mov_b32_e32 v43, v189
	v_mov_b32_e32 v44, v189
	v_mov_b32_e32 v45, v189
	v_mov_b32_e32 v46, 0
	v_mov_b32_e32 v47, v189
	v_mov_b32_e32 v48, v189
	v_mov_b32_e32 v49, v189
	v_mov_b32_e32 v50, 0
	v_mov_b32_e32 v51, v189
	v_mov_b32_e32 v52, v189
	v_mov_b32_e32 v53, v189
	v_mov_b32_e32 v54, 0
	v_mov_b32_e32 v55, v189
	v_mov_b32_e32 v56, v189
	v_mov_b32_e32 v57, v189
	v_mov_b32_e32 v58, 0
	v_mov_b32_e32 v59, v189
	v_mov_b32_e32 v60, v189
	v_mov_b32_e32 v61, v189
	v_mov_b32_e32 v62, 0
	v_mov_b32_e32 v63, v189
	v_mov_b32_e32 v64, v189
	v_mov_b32_e32 v65, v189
	s_waitcnt lgkmcnt(0)
	v_readfirstlane_b32 s27, v82
	s_mov_b64 s[28:29], 0
	s_add_i32 m0, s27, 0x8000
	s_nop 0
	global_load_lds_dwordx4 v[66:67], off
	s_add_i32 m0, s27, 0xc000
	s_nop 0
	global_load_lds_dwordx4 v[74:75], off
	s_add_i32 m0, s27, 0x9000
	s_nop 0
	global_load_lds_dwordx4 v[68:69], off
	s_add_i32 m0, s27, 0xd000
	s_nop 0
	global_load_lds_dwordx4 v[76:77], off
	s_add_i32 m0, s27, 0xa000
	s_nop 0
	global_load_lds_dwordx4 v[70:71], off
	s_add_i32 m0, s27, 0xe000
	s_nop 0
	global_load_lds_dwordx4 v[78:79], off
	s_add_i32 m0, s27, 0xb000
	s_nop 0
	global_load_lds_dwordx4 v[72:73], off
	s_add_i32 m0, s27, 0xf000
	s_nop 0
	global_load_lds_dwordx4 v[80:81], off
	s_movk_i32 s28, 0x80
	s_mov_b32 s24, 0
; __device__ __forceinline__ f32x4 mfma16(bf16x8 a, bf16x8 b, f32x4 c) { return __builtin_amdgcn_mfma_f32_16x16x32_bf16(a, b, c, 0, 0, 0); }
; __device__ __forceinline__ void gemm_acc(const bf16_t* __restrict__ A, long lda, const bf16_t* __restrict__ Bt, long ldb, int K, f32x4 (&acc)[4][4], char* lds) {
;     ...
;     for (int kt = 0; kt < nk; ++kt) {
;         char* cur = lds + (kt & 1) * 32768;
;         if (kt + 1 < nk) gemm_stage(A, lda, Bt, ldb, kt + 1, lds + ((kt + 1) & 1) * 32768, tid);
; #pragma unroll
;         for (int ks = 0; ks < 2; ++ks) {
;             bf16x8 af[4], bfr[4];
; #pragma unroll
;             for (int m = 0; m < 4; ++m) { const int row = wr * 64 + m * 16 + fr; af[m] = *reinterpret_cast<const bf16x8*>(cur + row * 128 + (((ks * 4 + fq) ^ (row & 7)) << 4)); }
; #pragma unroll
;             for (int n = 0; n < 4; ++n) { const int row = wc * 64 + n * 16 + fr; bfr[n] = *reinterpret_cast<const bf16x8*>(cur + 16384 + row * 128 + (((ks * 4 + fq) ^ (row & 7)) << 4)); }
;             __builtin_amdgcn_s_setprio(1);
; #pragma unroll
;             for (int m = 0; m < 4; ++m)
; #pragma unroll
;                 for (int n = 0; n < 4; ++n) acc[m][n] = mfma16(bfr[n], af[m], acc[m][n]);
;             __builtin_amdgcn_s_setprio(0);
;         }
;         asm volatile("s_waitcnt vmcnt(0)" ::: "memory");
;         __syncthreads();
;     }
.Lmy_mg_loop:
	s_waitcnt vmcnt(8)
	s_barrier
	s_and_b32 s26, s24, 1
	s_lshl_b32 s26, s26, 15
	v_add_u32_e32 v228, s26, v85
	v_add_u32_e32 v229, s26, v84
	v_add_u32_e32 v230, v228, v83
	v_add_u32_e32 v228, v228, v0
	v_add_u32_e32 v231, v229, v83
	v_add_u32_e32 v229, v229, v0
	ds_read_b128 v[86:89], v230
	ds_read_b128 v[90:93], v230 offset:2048
	ds_read_b128 v[94:97], v230 offset:4096
	ds_read_b128 v[98:101], v230 offset:6144
	ds_read_b128 v[190:193], v228 offset:16384
	ds_read_b128 v[194:197], v228 offset:18432
	ds_read_b128 v[198:201], v228 offset:20480
	ds_read_b128 v[202:205], v228 offset:22528
	ds_read_b128 v[162:165], v231
	ds_read_b128 v[166:169], v231 offset:2048
	ds_read_b128 v[170:173], v231 offset:4096
	ds_read_b128 v[174:177], v231 offset:6144
	ds_read_b128 v[206:209], v229 offset:16384
	ds_read_b128 v[210:213], v229 offset:18432
	ds_read_b128 v[214:217], v229 offset:20480
	ds_read_b128 v[222:225], v229 offset:22528
	s_waitcnt lgkmcnt(0)
	s_barrier
	s_cmp_ge_u32 s24, 14
	s_cbranch_scc1 .Lmy_mg_nodma
	s_add_i32 s26, s26, s27
	s_setprio 1
	v_mfma_f32_16x16x32_bf16 v[62:65], v[190:193], v[86:89], v[62:65]
	v_mfma_f32_16x16x32_bf16 v[58:61], v[194:197], v[86:89], v[58:61]
	v_mfma_f32_16x16x32_bf16 v[54:57], v[198:201], v[86:89], v[54:57]
	v_mfma_f32_16x16x32_bf16 v[50:53], v[202:205], v[86:89], v[50:53]
	s_add_i32 m0, s26, 0x0
	v_lshl_add_u64 v[226:227], v[66:67], 0, s[28:29]
	global_load_lds_dwordx4 v[226:227], off
	v_mfma_f32_16x16x32_bf16 v[46:49], v[190:193], v[90:93], v[46:49]
	v_mfma_f32_16x16x32_bf16 v[42:45], v[194:197], v[90:93], v[42:45]
	v_mfma_f32_16x16x32_bf16 v[38:41], v[198:201], v[90:93], v[38:41]
	v_mfma_f32_16x16x32_bf16 v[34:37], v[202:205], v[90:93], v[34:37]
	s_add_i32 m0, s26, 0x4000
	v_lshl_add_u64 v[226:227], v[74:75], 0, s[28:29]
	global_load_lds_dwordx4 v[226:227], off
	v_mfma_f32_16x16x32_bf16 v[30:33], v[190:193], v[94:97], v[30:33]
	v_mfma_f32_16x16x32_bf16 v[26:29], v[194:197], v[94:97], v[26:29]
	v_mfma_f32_16x16x32_bf16 v[22:25], v[198:201], v[94:97], v[22:25]
	v_mfma_f32_16x16x32_bf16 v[18:21], v[202:205], v[94:97], v[18:21]
	s_add_i32 m0, s26, 0x1000
	v_lshl_add_u64 v[226:227], v[68:69], 0, s[28:29]
	global_load_lds_dwordx4 v[226:227], off
	v_mfma_f32_16x16x32_bf16 v[14:17], v[190:193], v[98:101], v[14:17]
	v_mfma_f32_16x16x32_bf16 v[10:13], v[194:197], v[98:101], v[10:13]
	v_mfma_f32_16x16x32_bf16 v[6:9], v[198:201], v[98:101], v[6:9]
	v_mfma_f32_16x16x32_bf16 v[2:5], v[202:205], v[98:101], v[2:5]
	s_add_i32 m0, s26, 0x5000
	v_lshl_add_u64 v[226:227], v[76:77], 0, s[28:29]
	global_load_lds_dwordx4 v[226:227], off
	v_mfma_f32_16x16x32_bf16 v[62:65], v[206:209], v[162:165], v[62:65]
	v_mfma_f32_16x16x32_bf16 v[58:61], v[210:213], v[162:165], v[58:61]
	v_mfma_f32_16x16x32_bf16 v[54:57], v[214:217], v[162:165], v[54:57]
	v_mfma_f32_16x16x32_bf16 v[50:53], v[222:225], v[162:165], v[50:53]
	s_add_i32 m0, s26, 0x2000
	v_lshl_add_u64 v[226:227], v[70:71], 0, s[28:29]
	global_load_lds_dwordx4 v[226:227], off
	v_mfma_f32_16x16x32_bf16 v[46:49], v[206:209], v[166:169], v[46:49]
	v_mfma_f32_16x16x32_bf16 v[42:45], v[210:213], v[166:169], v[42:45]
	v_mfma_f32_16x16x32_bf16 v[38:41], v[214:217], v[166:169], v[38:41]
	v_mfma_f32_16x16x32_bf16 v[34:37], v[222:225], v[166:169], v[34:37]
	s_add_i32 m0, s26, 0x6000
	v_lshl_add_u64 v[226:227], v[78:79], 0, s[28:29]
	global_load_lds_dwordx4 v[226:227], off
	v_mfma_f32_16x16x32_bf16 v[30:33], v[206:209], v[170:173], v[30:33]
	v_mfma_f32_16x16x32_bf16 v[26:29], v[210:213], v[170:173], v[26:29]
	v_mfma_f32_16x16x32_bf16 v[22:25], v[214:217], v[170:173], v[22:25]
	v_mfma_f32_16x16x32_bf16 v[18:21], v[222:225], v[170:173], v[18:21]
	s_add_i32 m0, s26, 0x3000
	v_lshl_add_u64 v[226:227], v[72:73], 0, s[28:29]
	global_load_lds_dwordx4 v[226:227], off
	v_mfma_f32_16x16x32_bf16 v[14:17], v[206:209], v[174:177], v[14:17]
	v_mfma_f32_16x16x32_bf16 v[10:13], v[210:213], v[174:177], v[10:13]
	v_mfma_f32_16x16x32_bf16 v[6:9], v[214:217], v[174:177], v[6:9]
	v_mfma_f32_16x16x32_bf16 v[2:5], v[222:225], v[174:177], v[2:5]
	s_add_i32 m0, s26, 0x7000
	v_lshl_add_u64 v[226:227], v[80:81], 0, s[28:29]
	global_load_lds_dwordx4 v[226:227], off
	s_setprio 0
	s_add_u32 s28, s28, 0x80
	s_addc_u32 s29, s29, 0
	s_branch .Lmy_mg_join

; __device__ __forceinline__ f32x4 mfma16(bf16x8 a, bf16x8 b, f32x4 c) { return __builtin_amdgcn_mfma_f32_16x16x32_bf16(a, b, c, 0, 0, 0); }
; __device__ __forceinline__ void gemm_acc(const bf16_t* __restrict__ A, long lda, const bf16_t* __restrict__ Bt, long ldb, int K, f32x4 (&acc)[4][4], char* lds) {
;     ...
;     for (int kt = 0; kt < nk; ++kt) {
;         char* cur = lds + (kt & 1) * 32768;
;         if (kt + 1 < nk) gemm_stage(A, lda, Bt, ldb, kt + 1, lds + ((kt + 1) & 1) * 32768, tid);
; #pragma unroll
;         for (int ks = 0; ks < 2; ++ks) {
;             bf16x8 af[4], bfr[4];
; #pragma unroll
;             for (int m = 0; m < 4; ++m) { const int row = wr * 64 + m * 16 + fr; af[m] = *reinterpret_cast<const bf16x8*>(cur + row * 128 + (((ks * 4 + fq) ^ (row & 7)) << 4)); }
; #pragma unroll
;             for (int n = 0; n < 4; ++n) { const int row = wc * 64 + n * 16 + fr; bfr[n] = *reinterpret_cast<const bf16x8*>(cur + 16384 + row * 128 + (((ks * 4 + fq) ^ (row & 7)) << 4)); }
;             __builtin_amdgcn_s_setprio(1);
; #pragma unroll
;             for (int m = 0; m < 4; ++m)
; #pragma unroll
;                 for (int n = 0; n < 4; ++n) acc[m][n] = mfma16(bfr[n], af[m], acc[m][n]);
;             __builtin_amdgcn_s_setprio(0);
;         }
;         asm volatile("s_waitcnt vmcnt(0)" ::: "memory");
;         __syncthreads();
;     }
; __device__ void ph_gemm_merge(const Params& P, char* lds) {
;     ...
;             const size_t yoff = (n == 0) ? OFF_Y0 : (n == 1 ? OFF_YB : (n == 2 ? OFF_YC : OFF_YD));
;             const bf16_t* Y = (const bf16_t*)(P.ws + yoff);
;             f32x4 acc[4][4]; zero_acc(acc);
.Lmy_mg_join:
	s_add_i32 s24, s24, 1
	s_cmp_lt_u32 s24, 15
	s_cbranch_scc1 .Lmy_mg_loop
	s_waitcnt vmcnt(0)
	s_barrier
	s_mov_b32 s58, 0x8000
	v_add_u32_e32 v82, s58, v85
	v_add_u32_e32 v78, v82, v83
	v_add_u32_e32 v82, v82, v0
	ds_read_b128 v[66:69], v78
	ds_read_b128 v[70:73], v78 offset:2048
	ds_read_b128 v[74:77], v78 offset:4096
	ds_read_b128 v[78:81], v78 offset:6144
	ds_read_b128 v[86:89], v82 offset:16384
	ds_read_b128 v[90:93], v82 offset:18432
	ds_read_b128 v[94:97], v82 offset:20480
	ds_read_b128 v[98:101], v82 offset:22528
	s_setprio 1
	s_waitcnt lgkmcnt(3)
	v_mfma_f32_16x16x32_bf16 v[30:33], v[86:89], v[74:77], v[30:33]
	s_waitcnt lgkmcnt(2)
	v_mfma_f32_16x16x32_bf16 v[10:13], v[90:93], v[78:81], v[10:13]
	s_waitcnt lgkmcnt(1)
	v_mfma_f32_16x16x32_bf16 v[6:9], v[94:97], v[78:81], v[6:9]
	s_waitcnt lgkmcnt(0)
	v_mfma_f32_16x16x32_bf16 v[2:5], v[98:101], v[78:81], v[2:5]
	v_mfma_f32_16x16x32_bf16 v[62:65], v[86:89], v[66:69], v[62:65]
	v_mfma_f32_16x16x32_bf16 v[58:61], v[90:93], v[66:69], v[58:61]
	v_mfma_f32_16x16x32_bf16 v[54:57], v[94:97], v[66:69], v[54:57]
	v_mfma_f32_16x16x32_bf16 v[50:53], v[98:101], v[66:69], v[50:53]
	v_mfma_f32_16x16x32_bf16 v[46:49], v[86:89], v[70:73], v[46:49]
	v_mfma_f32_16x16x32_bf16 v[42:45], v[90:93], v[70:73], v[42:45]
	v_mfma_f32_16x16x32_bf16 v[38:41], v[94:97], v[70:73], v[38:41]
	v_mfma_f32_16x16x32_bf16 v[34:37], v[98:101], v[70:73], v[34:37]
	v_mfma_f32_16x16x32_bf16 v[26:29], v[90:93], v[74:77], v[26:29]
	v_mfma_f32_16x16x32_bf16 v[22:25], v[94:97], v[74:77], v[22:25]
	v_mfma_f32_16x16x32_bf16 v[18:21], v[98:101], v[74:77], v[18:21]
	v_mfma_f32_16x16x32_bf16 v[14:17], v[86:89], v[78:81], v[14:17]
	s_setprio 0
	v_add_u32_e32 v82, s58, v84
	v_add_u32_e32 v78, v82, v83
	v_add_u32_e32 v0, v82, v0
	ds_read_b128 v[66:69], v78
	ds_read_b128 v[70:73], v78 offset:2048
	ds_read_b128 v[74:77], v78 offset:4096
	ds_read_b128 v[78:81], v78 offset:6144
	ds_read_b128 v[162:165], v0 offset:16384
	ds_read_b128 v[166:169], v0 offset:18432
	ds_read_b128 v[170:173], v0 offset:20480
	ds_read_b128 v[174:177], v0 offset:22528
	s_setprio 1
	s_waitcnt lgkmcnt(3)
	v_mfma_f32_16x16x32_bf16 v[126:129], v[162:165], v[66:69], v[62:65]
	s_waitcnt lgkmcnt(2)
	v_mfma_f32_16x16x32_bf16 v[122:125], v[166:169], v[66:69], v[58:61]
	s_waitcnt lgkmcnt(1)
	v_mfma_f32_16x16x32_bf16 v[118:121], v[170:173], v[66:69], v[54:57]
	s_waitcnt lgkmcnt(0)
	v_mfma_f32_16x16x32_bf16 v[114:117], v[174:177], v[66:69], v[50:53]
	v_mfma_f32_16x16x32_bf16 v[110:113], v[162:165], v[70:73], v[46:49]
	v_mfma_f32_16x16x32_bf16 v[106:109], v[166:169], v[70:73], v[42:45]
	v_mfma_f32_16x16x32_bf16 v[102:105], v[170:173], v[70:73], v[38:41]
	v_mfma_f32_16x16x32_bf16 v[98:101], v[174:177], v[70:73], v[34:37]
	v_mfma_f32_16x16x32_bf16 v[94:97], v[162:165], v[74:77], v[30:33]
	v_mfma_f32_16x16x32_bf16 v[90:93], v[166:169], v[74:77], v[26:29]
	v_mfma_f32_16x16x32_bf16 v[86:89], v[170:173], v[74:77], v[22:25]
	v_mfma_f32_16x16x32_bf16 v[82:85], v[174:177], v[74:77], v[18:21]
	v_mfma_f32_16x16x32_bf16 v[30:33], v[162:165], v[78:81], v[14:17]
	v_mfma_f32_16x16x32_bf16 v[10:13], v[166:169], v[78:81], v[10:13]
	v_mfma_f32_16x16x32_bf16 v[6:9], v[170:173], v[78:81], v[6:9]
	v_mfma_f32_16x16x32_bf16 v[2:5], v[174:177], v[78:81], v[2:5]
	s_setprio 0
	s_waitcnt vmcnt(0)
	s_cmp_lt_i32 s63, 1
	s_mov_b64 s[28:29], 0x24800000
	s_barrier
	s_cbranch_scc1 .LBB0_318
	s_cmp_lg_u32 s63, 1
	s_mov_b64 s[58:59], -1
	s_cbranch_scc0 .LBB0_315
	s_cmp_eq_u32 s63, 2
	s_mov_b32 s24, 0x20800000
	s_cselect_b32 s24, s24, 0x22800000
	s_mov_b64 s[58:59], 0
	s_mov_b64 s[28:29], s[24:25]

; __device__ __forceinline__ f32x4 mfma16(bf16x8 a, bf16x8 b, f32x4 c) { return __builtin_amdgcn_mfma_f32_16x16x32_bf16(a, b, c, 0, 0, 0); }
; __device__ __forceinline__ void gemm_acc2(const bf16_t* __restrict__ A, long lda, const bf16_t* __restrict__ Bt, long ldb, int K, f32x4 (&acc)[8][4], char* lds) {
;     ...
;     for (int kt = 0; kt < nk; ++kt) {
;         char* cur = lds + (kt & 1) * 24576;
;         if (kt + 1 < nk) gemm2_stage(A, lda, Bt, ldb, kt + 1, lds + ((kt + 1) & 1) * 24576, tid);
;         bf16x8 bfr[4];
; #pragma unroll
;         for (int n = 0; n < 4; ++n) { const int row = wc * 64 + n * 16 + fr; bfr[n] = *reinterpret_cast<const bf16x8*>(cur + 16384 + row * 64 + ((fq ^ ((row >> 2) & 3)) << 4)); }
;         bf16x8 af[8];
; #pragma unroll
;         for (int m = 0; m < 8; ++m) { const int row = wr * 128 + m * 16 + fr; af[m] = *reinterpret_cast<const bf16x8*>(cur + row * 64 + ((fq ^ ((row >> 2) & 3)) << 4)); }
;         __builtin_amdgcn_s_setprio(1);
; #pragma unroll
;         for (int m = 0; m < 8; ++m)
; #pragma unroll
;             for (int n = 0; n < 4; ++n) acc[m][n] = mfma16(bfr[n], af[m], acc[m][n]);
;         __builtin_amdgcn_s_setprio(0);
;         asm volatile("s_waitcnt vmcnt(0)" ::: "memory");
;         __syncthreads();
;     }
.Lmy_down_loop:
	s_waitcnt vmcnt(0)
	s_barrier
	ds_read_b128 v[130:133], v233
	ds_read_b128 v[134:137], v233 offset:2048
	ds_read_b128 v[138:141], v233 offset:4096
	ds_read_b128 v[142:145], v233 offset:6144
	ds_read_b128 v[146:149], v234
	ds_read_b128 v[150:153], v234 offset:2048
	ds_read_b128 v[154:157], v234 offset:4096
	ds_read_b128 v[158:161], v234 offset:6144
	ds_read_b128 v[162:165], v231
	ds_read_b128 v[166:169], v231 offset:2048
	ds_read_b128 v[170:173], v231 offset:4096
	ds_read_b128 v[174:177], v231 offset:6144
	ds_read_b128 v[182:185], v231 offset:8192
	ds_read_b128 v[186:189], v231 offset:10240
	ds_read_b128 v[190:193], v231 offset:12288
	ds_read_b128 v[194:197], v231 offset:14336
	ds_read_b128 v[198:201], v232
	ds_read_b128 v[202:205], v232 offset:2048
	ds_read_b128 v[206:209], v232 offset:4096
	ds_read_b128 v[210:213], v232 offset:6144
	ds_read_b128 v[214:217], v232 offset:8192
	ds_read_b128 v[218:221], v232 offset:10240
	ds_read_b128 v[222:225], v232 offset:12288
	ds_read_b128 v[226:229], v232 offset:14336
	s_add_u32 s0, s0, 0x80
	s_addc_u32 s1, s1, 0
	s_add_u32 s34, s34, 0x80
	s_addc_u32 s35, s35, 0
	s_waitcnt lgkmcnt(0)
	s_barrier
	s_setprio 1
	v_mfma_f32_16x16x32_bf16 v[126:129], v[130:133], v[162:165], v[126:129]
	v_mfma_f32_16x16x32_bf16 v[122:125], v[134:137], v[162:165], v[122:125]
	v_mfma_f32_16x16x32_bf16 v[118:121], v[138:141], v[162:165], v[118:121]
	v_mfma_f32_16x16x32_bf16 v[54:57], v[142:145], v[162:165], v[54:57]
	s_add_i32 m0, s39, 0x0
	s_add_u32 s26, s0, 0x0
	s_addc_u32 s27, s1, 0
	global_load_lds_dwordx4 v230, s[26:27]
	v_mfma_f32_16x16x32_bf16 v[114:117], v[130:133], v[166:169], v[114:117]
	v_mfma_f32_16x16x32_bf16 v[110:113], v[134:137], v[166:169], v[110:113]
	v_mfma_f32_16x16x32_bf16 v[106:109], v[138:141], v[166:169], v[106:109]
	v_mfma_f32_16x16x32_bf16 v[30:33], v[142:145], v[166:169], v[30:33]
	s_add_i32 m0, s39, 0x1000
	s_add_u32 s26, s0, 0x2c000
	s_addc_u32 s27, s1, 0
	global_load_lds_dwordx4 v230, s[26:27]
	v_mfma_f32_16x16x32_bf16 v[102:105], v[130:133], v[170:173], v[102:105]
	v_mfma_f32_16x16x32_bf16 v[98:101], v[134:137], v[170:173], v[98:101]
	v_mfma_f32_16x16x32_bf16 v[94:97], v[138:141], v[170:173], v[94:97]
	v_mfma_f32_16x16x32_bf16 v[22:25], v[142:145], v[170:173], v[22:25]
	s_add_i32 m0, s39, 0x2000
	s_add_u32 s26, s0, 0x58000
	s_addc_u32 s27, s1, 0
	global_load_lds_dwordx4 v230, s[26:27]
	v_mfma_f32_16x16x32_bf16 v[90:93], v[130:133], v[174:177], v[90:93]
	v_mfma_f32_16x16x32_bf16 v[86:89], v[134:137], v[174:177], v[86:89]
	v_mfma_f32_16x16x32_bf16 v[82:85], v[138:141], v[174:177], v[82:85]
	v_mfma_f32_16x16x32_bf16 v[18:21], v[142:145], v[174:177], v[18:21]
	s_add_i32 m0, s39, 0x3000
	s_add_u32 s26, s0, 0x84000
	s_addc_u32 s27, s1, 0
	global_load_lds_dwordx4 v230, s[26:27]
	v_mfma_f32_16x16x32_bf16 v[78:81], v[130:133], v[182:185], v[78:81]
	v_mfma_f32_16x16x32_bf16 v[74:77], v[134:137], v[182:185], v[74:77]
	v_mfma_f32_16x16x32_bf16 v[70:73], v[138:141], v[182:185], v[70:73]
	v_mfma_f32_16x16x32_bf16 v[14:17], v[142:145], v[182:185], v[14:17]
	s_add_i32 m0, s39, 0x4000
	s_add_u32 s26, s0, 0xb0000
	s_addc_u32 s27, s1, 0
	global_load_lds_dwordx4 v230, s[26:27]
	v_mfma_f32_16x16x32_bf16 v[66:69], v[130:133], v[186:189], v[66:69]
	v_mfma_f32_16x16x32_bf16 v[62:65], v[134:137], v[186:189], v[62:65]
	v_mfma_f32_16x16x32_bf16 v[58:61], v[138:141], v[186:189], v[58:61]
	v_mfma_f32_16x16x32_bf16 v[10:13], v[142:145], v[186:189], v[10:13]
	s_add_i32 m0, s39, 0x5000
	s_add_u32 s26, s0, 0xdc000
	s_addc_u32 s27, s1, 0
	global_load_lds_dwordx4 v230, s[26:27]
	v_mfma_f32_16x16x32_bf16 v[50:53], v[130:133], v[190:193], v[50:53]
	v_mfma_f32_16x16x32_bf16 v[46:49], v[134:137], v[190:193], v[46:49]
	v_mfma_f32_16x16x32_bf16 v[42:45], v[138:141], v[190:193], v[42:45]
	v_mfma_f32_16x16x32_bf16 v[6:9], v[142:145], v[190:193], v[6:9]
	s_add_i32 m0, s39, 0x6000
	s_add_u32 s26, s0, 0x108000
	s_addc_u32 s27, s1, 0
	global_load_lds_dwordx4 v230, s[26:27]
	v_mfma_f32_16x16x32_bf16 v[38:41], v[130:133], v[194:197], v[38:41]
	v_mfma_f32_16x16x32_bf16 v[34:37], v[134:137], v[194:197], v[34:37]
	v_mfma_f32_16x16x32_bf16 v[26:29], v[138:141], v[194:197], v[26:29]
	v_mfma_f32_16x16x32_bf16 v[2:5], v[142:145], v[194:197], v[2:5]
	s_add_i32 m0, s39, 0x7000
	s_add_u32 s26, s0, 0x134000
	s_addc_u32 s27, s1, 0
	global_load_lds_dwordx4 v230, s[26:27]
	v_mfma_f32_16x16x32_bf16 v[126:129], v[146:149], v[198:201], v[126:129]
	v_mfma_f32_16x16x32_bf16 v[122:125], v[150:153], v[198:201], v[122:125]
	v_mfma_f32_16x16x32_bf16 v[118:121], v[154:157], v[198:201], v[118:121]
	v_mfma_f32_16x16x32_bf16 v[54:57], v[158:161], v[198:201], v[54:57]
	s_add_i32 m0, s39, 0x8000
	s_add_u32 s26, s34, 0x0
	s_addc_u32 s27, s35, 0
	global_load_lds_dwordx4 v230, s[26:27]
	v_mfma_f32_16x16x32_bf16 v[114:117], v[146:149], v[202:205], v[114:117]
	v_mfma_f32_16x16x32_bf16 v[110:113], v[150:153], v[202:205], v[110:113]
	v_mfma_f32_16x16x32_bf16 v[106:109], v[154:157], v[202:205], v[106:109]
	v_mfma_f32_16x16x32_bf16 v[30:33], v[158:161], v[202:205], v[30:33]
	s_add_i32 m0, s39, 0x9000
	s_add_u32 s26, s34, 0x2c000
	s_addc_u32 s27, s35, 0
	global_load_lds_dwordx4 v230, s[26:27]
	v_mfma_f32_16x16x32_bf16 v[102:105], v[146:149], v[206:209], v[102:105]
	v_mfma_f32_16x16x32_bf16 v[98:101], v[150:153], v[206:209], v[98:101]
	v_mfma_f32_16x16x32_bf16 v[94:97], v[154:157], v[206:209], v[94:97]
	v_mfma_f32_16x16x32_bf16 v[22:25], v[158:161], v[206:209], v[22:25]
	s_add_i32 m0, s39, 0xa000
	s_add_u32 s26, s34, 0x58000
	s_addc_u32 s27, s35, 0
	global_load_lds_dwordx4 v230, s[26:27]
	v_mfma_f32_16x16x32_bf16 v[90:93], v[146:149], v[210:213], v[90:93]
; __device__ __forceinline__ f32x4 mfma16(bf16x8 a, bf16x8 b, f32x4 c) { return __builtin_amdgcn_mfma_f32_16x16x32_bf16(a, b, c, 0, 0, 0); }
; __device__ __forceinline__ void gemm_acc2(const bf16_t* __restrict__ A, long lda, const bf16_t* __restrict__ Bt, long ldb, int K, f32x4 (&acc)[8][4], char* lds) {
;     ...
;     for (int kt = 0; kt < nk; ++kt) {
;         char* cur = lds + (kt & 1) * 24576;
;         if (kt + 1 < nk) gemm2_stage(A, lda, Bt, ldb, kt + 1, lds + ((kt + 1) & 1) * 24576, tid);
;         bf16x8 bfr[4];
; #pragma unroll
;         for (int n = 0; n < 4; ++n) { const int row = wc * 64 + n * 16 + fr; bfr[n] = *reinterpret_cast<const bf16x8*>(cur + 16384 + row * 64 + ((fq ^ ((row >> 2) & 3)) << 4)); }
;         bf16x8 af[8];
; #pragma unroll
;         for (int m = 0; m < 8; ++m) { const int row = wr * 128 + m * 16 + fr; af[m] = *reinterpret_cast<const bf16x8*>(cur + row * 64 + ((fq ^ ((row >> 2) & 3)) << 4)); }
;         __builtin_amdgcn_s_setprio(1);
; #pragma unroll
;         for (int m = 0; m < 8; ++m)
; #pragma unroll
;             for (int n = 0; n < 4; ++n) acc[m][n] = mfma16(bfr[n], af[m], acc[m][n]);
;         __builtin_amdgcn_s_setprio(0);
;         asm volatile("s_waitcnt vmcnt(0)" ::: "memory");
;         __syncthreads();
;     }
	v_mfma_f32_16x16x32_bf16 v[86:89], v[150:153], v[210:213], v[86:89]
	v_mfma_f32_16x16x32_bf16 v[82:85], v[154:157], v[210:213], v[82:85]
	v_mfma_f32_16x16x32_bf16 v[18:21], v[158:161], v[210:213], v[18:21]
	s_add_i32 m0, s39, 0xb000
	s_add_u32 s26, s34, 0x84000
	s_addc_u32 s27, s35, 0
	global_load_lds_dwordx4 v230, s[26:27]
	v_mfma_f32_16x16x32_bf16 v[78:81], v[146:149], v[214:217], v[78:81]
	v_mfma_f32_16x16x32_bf16 v[74:77], v[150:153], v[214:217], v[74:77]
	v_mfma_f32_16x16x32_bf16 v[70:73], v[154:157], v[214:217], v[70:73]
	v_mfma_f32_16x16x32_bf16 v[14:17], v[158:161], v[214:217], v[14:17]
	v_mfma_f32_16x16x32_bf16 v[66:69], v[146:149], v[218:221], v[66:69]
	v_mfma_f32_16x16x32_bf16 v[62:65], v[150:153], v[218:221], v[62:65]
	v_mfma_f32_16x16x32_bf16 v[58:61], v[154:157], v[218:221], v[58:61]
	v_mfma_f32_16x16x32_bf16 v[10:13], v[158:161], v[218:221], v[10:13]
	v_mfma_f32_16x16x32_bf16 v[50:53], v[146:149], v[222:225], v[50:53]
	v_mfma_f32_16x16x32_bf16 v[46:49], v[150:153], v[222:225], v[46:49]
	v_mfma_f32_16x16x32_bf16 v[42:45], v[154:157], v[222:225], v[42:45]
	v_mfma_f32_16x16x32_bf16 v[6:9], v[158:161], v[222:225], v[6:9]
	v_mfma_f32_16x16x32_bf16 v[38:41], v[146:149], v[226:229], v[38:41]
	v_mfma_f32_16x16x32_bf16 v[34:37], v[150:153], v[226:229], v[34:37]
	v_mfma_f32_16x16x32_bf16 v[26:29], v[154:157], v[226:229], v[26:29]
	v_mfma_f32_16x16x32_bf16 v[2:5], v[158:161], v[226:229], v[2:5]
	s_setprio 0
	s_add_i32 s38, s38, 1
	s_cmp_lt_u32 s38, 43
	s_cbranch_scc1 .Lmy_down_loop
	s_waitcnt vmcnt(0)
	s_barrier
	ds_read_b128 v[130:133], v233
	ds_read_b128 v[134:137], v233 offset:2048
	ds_read_b128 v[138:141], v233 offset:4096
	ds_read_b128 v[142:145], v233 offset:6144
	ds_read_b128 v[146:149], v234
	ds_read_b128 v[150:153], v234 offset:2048
	ds_read_b128 v[154:157], v234 offset:4096
	ds_read_b128 v[158:161], v234 offset:6144
	ds_read_b128 v[162:165], v231
	ds_read_b128 v[166:169], v231 offset:2048
	ds_read_b128 v[170:173], v231 offset:4096
	ds_read_b128 v[174:177], v231 offset:6144
	ds_read_b128 v[182:185], v231 offset:8192
	ds_read_b128 v[186:189], v231 offset:10240
	ds_read_b128 v[190:193], v231 offset:12288
	ds_read_b128 v[194:197], v231 offset:14336
	ds_read_b128 v[198:201], v232
	ds_read_b128 v[202:205], v232 offset:2048
	ds_read_b128 v[206:209], v232 offset:4096
	ds_read_b128 v[210:213], v232 offset:6144
	ds_read_b128 v[214:217], v232 offset:8192
	ds_read_b128 v[218:221], v232 offset:10240
	ds_read_b128 v[222:225], v232 offset:12288
	ds_read_b128 v[226:229], v232 offset:14336
	s_waitcnt lgkmcnt(0)
	s_setprio 1
	v_mfma_f32_16x16x32_bf16 v[126:129], v[130:133], v[162:165], v[126:129]
	v_mfma_f32_16x16x32_bf16 v[122:125], v[134:137], v[162:165], v[122:125]
	v_mfma_f32_16x16x32_bf16 v[118:121], v[138:141], v[162:165], v[118:121]
	v_mfma_f32_16x16x32_bf16 v[54:57], v[142:145], v[162:165], v[54:57]
	v_mfma_f32_16x16x32_bf16 v[114:117], v[130:133], v[166:169], v[114:117]
	v_mfma_f32_16x16x32_bf16 v[110:113], v[134:137], v[166:169], v[110:113]
	v_mfma_f32_16x16x32_bf16 v[106:109], v[138:141], v[166:169], v[106:109]
	v_mfma_f32_16x16x32_bf16 v[30:33], v[142:145], v[166:169], v[30:33]
	v_mfma_f32_16x16x32_bf16 v[102:105], v[130:133], v[170:173], v[102:105]
	v_mfma_f32_16x16x32_bf16 v[98:101], v[134:137], v[170:173], v[98:101]
	v_mfma_f32_16x16x32_bf16 v[94:97], v[138:141], v[170:173], v[94:97]
	v_mfma_f32_16x16x32_bf16 v[22:25], v[142:145], v[170:173], v[22:25]
	v_mfma_f32_16x16x32_bf16 v[90:93], v[130:133], v[174:177], v[90:93]
	v_mfma_f32_16x16x32_bf16 v[86:89], v[134:137], v[174:177], v[86:89]
	v_mfma_f32_16x16x32_bf16 v[82:85], v[138:141], v[174:177], v[82:85]
	v_mfma_f32_16x16x32_bf16 v[18:21], v[142:145], v[174:177], v[18:21]
	v_mfma_f32_16x16x32_bf16 v[78:81], v[130:133], v[182:185], v[78:81]
	v_mfma_f32_16x16x32_bf16 v[74:77], v[134:137], v[182:185], v[74:77]
	v_mfma_f32_16x16x32_bf16 v[70:73], v[138:141], v[182:185], v[70:73]
	v_mfma_f32_16x16x32_bf16 v[14:17], v[142:145], v[182:185], v[14:17]
	v_mfma_f32_16x16x32_bf16 v[66:69], v[130:133], v[186:189], v[66:69]
	v_mfma_f32_16x16x32_bf16 v[62:65], v[134:137], v[186:189], v[62:65]
	v_mfma_f32_16x16x32_bf16 v[58:61], v[138:141], v[186:189], v[58:61]
	v_mfma_f32_16x16x32_bf16 v[10:13], v[142:145], v[186:189], v[10:13]
	v_mfma_f32_16x16x32_bf16 v[50:53], v[130:133], v[190:193], v[50:53]
	v_mfma_f32_16x16x32_bf16 v[46:49], v[134:137], v[190:193], v[46:49]
	v_mfma_f32_16x16x32_bf16 v[42:45], v[138:141], v[190:193], v[42:45]
	v_mfma_f32_16x16x32_bf16 v[6:9], v[142:145], v[190:193], v[6:9]
	v_mfma_f32_16x16x32_bf16 v[38:41], v[130:133], v[194:197], v[38:41]
	v_mfma_f32_16x16x32_bf16 v[34:37], v[134:137], v[194:197], v[34:37]
	v_mfma_f32_16x16x32_bf16 v[26:29], v[138:141], v[194:197], v[26:29]
	v_mfma_f32_16x16x32_bf16 v[2:5], v[142:145], v[194:197], v[2:5]
	v_mfma_f32_16x16x32_bf16 v[126:129], v[146:149], v[198:201], v[126:129]
	v_mfma_f32_16x16x32_bf16 v[122:125], v[150:153], v[198:201], v[122:125]
	v_mfma_f32_16x16x32_bf16 v[118:121], v[154:157], v[198:201], v[118:121]
	v_mfma_f32_16x16x32_bf16 v[54:57], v[158:161], v[198:201], v[54:57]
	v_mfma_f32_16x16x32_bf16 v[114:117], v[146:149], v[202:205], v[114:117]
	v_mfma_f32_16x16x32_bf16 v[110:113], v[150:153], v[202:205], v[110:113]
	v_mfma_f32_16x16x32_bf16 v[106:109], v[154:157], v[202:205], v[106:109]
	v_mfma_f32_16x16x32_bf16 v[30:33], v[158:161], v[202:205], v[30:33]
	v_mfma_f32_16x16x32_bf16 v[102:105], v[146:149], v[206:209], v[102:105]
	v_mfma_f32_16x16x32_bf16 v[98:101], v[150:153], v[206:209], v[98:101]
	v_mfma_f32_16x16x32_bf16 v[94:97], v[154:157], v[206:209], v[94:97]
	v_mfma_f32_16x16x32_bf16 v[22:25], v[158:161], v[206:209], v[22:25]
; __device__ __forceinline__ int tid_() { int x = threadIdx.x; asm volatile("" : "+v"(x)); return x; }
; __device__ __forceinline__ void resid_tile2(const f32x4 (&acc)[8][4], float* __restrict__ h, int row0, int col0, const float* __restrict__ gate) {
;     const int tid = tid_(), wid = tid >> 6, lane = tid & 63, wr = wid >> 1, wc = wid & 1, fr = lane & 15, fq = lane >> 4;
;     const int b = row0 >> 11;
; #pragma unroll
;     for (int n = 0; n < 4; ++n) {
;         const int col = col0 + wc * 64 + n * 16 + fq * 4;
;         const f32x4 gv = *(const f32x4*)(gate + (size_t)b * 6144 + col);
; #pragma unroll
;         for (int m = 0; m < 8; ++m) {
;             float* hp = h + (size_t)(row0 + wr * 128 + m * 16 + fr) * DM + col;
;             const f32x4 o = *(const f32x4*)hp + gv * acc[m][n];
;             *(f32x4*)hp = o;
;         }
;     }
; }
	v_mfma_f32_16x16x32_bf16 v[90:93], v[146:149], v[210:213], v[90:93]
	v_mfma_f32_16x16x32_bf16 v[86:89], v[150:153], v[210:213], v[86:89]
	v_mfma_f32_16x16x32_bf16 v[82:85], v[154:157], v[210:213], v[82:85]
	v_mfma_f32_16x16x32_bf16 v[18:21], v[158:161], v[210:213], v[18:21]
	v_mfma_f32_16x16x32_bf16 v[78:81], v[146:149], v[214:217], v[78:81]
	v_mfma_f32_16x16x32_bf16 v[74:77], v[150:153], v[214:217], v[74:77]
	v_mfma_f32_16x16x32_bf16 v[70:73], v[154:157], v[214:217], v[70:73]
	v_mfma_f32_16x16x32_bf16 v[14:17], v[158:161], v[214:217], v[14:17]
	v_mfma_f32_16x16x32_bf16 v[66:69], v[146:149], v[218:221], v[66:69]
	v_mfma_f32_16x16x32_bf16 v[62:65], v[150:153], v[218:221], v[62:65]
	v_mfma_f32_16x16x32_bf16 v[58:61], v[154:157], v[218:221], v[58:61]
	v_mfma_f32_16x16x32_bf16 v[10:13], v[158:161], v[218:221], v[10:13]
	v_mfma_f32_16x16x32_bf16 v[50:53], v[146:149], v[222:225], v[50:53]
	v_mfma_f32_16x16x32_bf16 v[46:49], v[150:153], v[222:225], v[46:49]
	v_mfma_f32_16x16x32_bf16 v[42:45], v[154:157], v[222:225], v[42:45]
	v_mfma_f32_16x16x32_bf16 v[6:9], v[158:161], v[222:225], v[6:9]
	v_mfma_f32_16x16x32_bf16 v[38:41], v[146:149], v[226:229], v[38:41]
	v_mfma_f32_16x16x32_bf16 v[34:37], v[150:153], v[226:229], v[34:37]
	v_mfma_f32_16x16x32_bf16 v[26:29], v[154:157], v[226:229], v[26:29]
	v_mfma_f32_16x16x32_bf16 v[2:5], v[158:161], v[226:229], v[2:5]
	s_setprio 0
	v_mov_b32_e32 v182, 0x2c60000
	v_mov_b32_e32 v183, 0x540
	v_mov_b32_e32 v184, 0x6000
	v_mov_b32_e32 v185, 0x2000
	v_mov_b32_e32 v186, 0x160000
	v_mov_b32_e32 v187, 0x70
	v_mov_b32_e32 v188, 0x1100
	v_mov_b32_e32 v218, 0
	v_mov_b32_e32 v219, 0
	v_mov_b32_e32 v220, 0
	v_mov_b32_e32 v221, 0
	s_nop 7
	s_nop 7
	v_mov_b32_e32 v146, v102
	v_mov_b32_e32 v147, v103
	v_mov_b32_e32 v148, v104
	v_mov_b32_e32 v149, v105
	v_mov_b32_e32 v150, v78
	v_mov_b32_e32 v151, v79
	v_mov_b32_e32 v152, v80
	v_mov_b32_e32 v153, v81
	v_mov_b32_e32 v154, v66
	v_mov_b32_e32 v155, v67
	v_mov_b32_e32 v156, v68
	v_mov_b32_e32 v157, v69
	v_mov_b32_e32 v158, v50
	v_mov_b32_e32 v159, v51
	v_mov_b32_e32 v160, v52
	v_mov_b32_e32 v161, v53
	v_mov_b32_e32 v0, v178
	s_waitcnt vmcnt(0)
	s_barrier
	s_lshl_b32 s0, s30, 7
	v_lshrrev_b32_e32 v51, 2, v0
	v_and_b32_e32 v50, 64, v0
	v_and_b32_e32 v51, 12, v51
	v_or3_b32 v50, v50, s0, v51
	v_and_b32_e32 v51, 0xffffff80, v0
	s_ashr_i32 s1, s29, 3
	v_lshl_add_u32 v51, s29, 8, v51
	s_mul_hi_i32 s26, s1, 0x6000
	s_mulk_i32 s1, 0x6000
	v_and_or_b32 v104, v0, 15, v51
	v_ashrrev_i32_e32 v51, 31, v50
	v_readlane_b32 s48, v241, 13
	s_add_u32 s0, s24, s1
	v_ashrrev_i32_e32 v105, 31, v104
	v_lshlrev_b64 v[50:51], 2, v[50:51]
	v_readlane_b32 s50, v241, 15
	v_readlane_b32 s51, v241, 16
	s_addc_u32 s1, s28, s26
	v_lshlrev_b64 v[52:53], 12, v[104:105]
	v_lshl_add_u64 v[134:135], s[50:51], 0, v[50:51]
	v_lshl_add_u64 v[102:103], s[0:1], 0, v[50:51]
	v_lshl_add_u64 v[68:69], v[134:135], 0, v[52:53]
	v_readlane_b32 s0, v239, 10
	s_add_i32 s21, s21, s0
	v_readlane_b32 s49, v241, 14
	v_readlane_b32 s1, v239, 11
	s_mov_b32 s26, 0x10000
	s_mov_b32 s27, 0
	v_lshl_add_u64 v[222:223], v[68:69], 0, s[26:27]
	v_lshl_add_u64 v[224:225], v[222:223], 0, s[26:27]
	v_lshl_add_u64 v[226:227], v[224:225], 0, s[26:27]
	v_lshl_add_u64 v[228:229], v[226:227], 0, s[26:27]
	v_lshl_add_u64 v[230:231], v[228:229], 0, s[26:27]
	v_lshl_add_u64 v[232:233], v[230:231], 0, s[26:27]
	v_lshl_add_u64 v[234:235], v[232:233], 0, s[26:27]
	global_load_dwordx4 v[190:193], v[102:103], off
	global_load_dwordx4 v[130:133], v[68:69], off
	global_load_dwordx4 v[134:137], v[222:223], off
	global_load_dwordx4 v[138:141], v[224:225], off
	global_load_dwordx4 v[142:145], v[226:227], off
	global_load_dwordx4 v[162:165], v[228:229], off
	global_load_dwordx4 v[166:169], v[230:231], off
	global_load_dwordx4 v[170:173], v[232:233], off
	global_load_dwordx4 v[174:177], v[234:235], off
	s_waitcnt vmcnt(7)
	v_pk_fma_f32 v[132:133], v[128:129], v[192:193], v[132:133]
	v_pk_fma_f32 v[130:131], v[126:127], v[190:191], v[130:131]
	global_store_dwordx4 v[68:69], v[130:133], off
	s_waitcnt vmcnt(7)
	v_pk_fma_f32 v[136:137], v[116:117], v[192:193], v[136:137]
	v_pk_fma_f32 v[134:135], v[114:115], v[190:191], v[134:135]
	global_store_dwordx4 v[222:223], v[134:137], off
	s_waitcnt vmcnt(7)
	v_pk_fma_f32 v[140:141], v[148:149], v[192:193], v[140:141]
	v_pk_fma_f32 v[138:139], v[146:147], v[190:191], v[138:139]
	global_store_dwordx4 v[224:225], v[138:141], off
	s_waitcnt vmcnt(7)
	v_pk_fma_f32 v[144:145], v[92:93], v[192:193], v[144:145]
	v_pk_fma_f32 v[142:143], v[90:91], v[190:191], v[142:143]
	global_store_dwordx4 v[226:227], v[142:145], off
	s_waitcnt vmcnt(7)
	v_pk_fma_f32 v[164:165], v[152:153], v[192:193], v[164:165]
	v_pk_fma_f32 v[162:163], v[150:151], v[190:191], v[162:163]
	global_store_dwordx4 v[228:229], v[162:165], off
	s_waitcnt vmcnt(7)
	v_pk_fma_f32 v[168:169], v[156:157], v[192:193], v[168:169]
	v_pk_fma_f32 v[166:167], v[154:155], v[190:191], v[166:167]
	global_store_dwordx4 v[230:231], v[166:169], off
	s_waitcnt vmcnt(7)
	v_pk_fma_f32 v[172:173], v[160:161], v[192:193], v[172:173]
	v_pk_fma_f32 v[170:171], v[158:159], v[190:191], v[170:171]
	global_store_dwordx4 v[232:233], v[170:173], off
	s_waitcnt vmcnt(7)
	v_pk_fma_f32 v[176:177], v[40:41], v[192:193], v[176:177]
	v_pk_fma_f32 v[174:175], v[38:39], v[190:191], v[174:175]
	global_store_dwordx4 v[234:235], v[174:177], off
	global_load_dwordx4 v[194:197], v[102:103], off offset:64
	global_load_dwordx4 v[130:133], v[68:69], off offset:64
	global_load_dwordx4 v[134:137], v[222:223], off offset:64
	global_load_dwordx4 v[138:141], v[224:225], off offset:64
	global_load_dwordx4 v[142:145], v[226:227], off offset:64
	global_load_dwordx4 v[162:165], v[228:229], off offset:64
	global_load_dwordx4 v[166:169], v[230:231], off offset:64
	global_load_dwordx4 v[170:173], v[232:233], off offset:64
	global_load_dwordx4 v[174:177], v[234:235], off offset:64
	s_waitcnt vmcnt(7)
; __device__ __forceinline__ int tid_() { int x = threadIdx.x; asm volatile("" : "+v"(x)); return x; }
; __device__ __forceinline__ int bid_() { int x = blockIdx.x; asm volatile("" : "+s"(x)); return x; }
; __device__ __forceinline__ void resid_tile2(const f32x4 (&acc)[8][4], float* __restrict__ h, int row0, int col0, const float* __restrict__ gate) {
;     const int tid = tid_(), wid = tid >> 6, lane = tid & 63, wr = wid >> 1, wc = wid & 1, fr = lane & 15, fq = lane >> 4;
;     const int b = row0 >> 11;
; #pragma unroll
;     for (int n = 0; n < 4; ++n) {
;         const int col = col0 + wc * 64 + n * 16 + fq * 4;
;         const f32x4 gv = *(const f32x4*)(gate + (size_t)b * 6144 + col);
; #pragma unroll
;         for (int m = 0; m < 8; ++m) {
;             float* hp = h + (size_t)(row0 + wr * 128 + m * 16 + fr) * DM + col;
;             const f32x4 o = *(const f32x4*)hp + gv * acc[m][n];
;             *(f32x4*)hp = o;
;         }
;     }
; }
; __device__ void ph_gemm_down(const Params& P, int l, char* lds) {
;     ...
;     for (int item = bid_(); item < 128 * 8; item += gridDim.x) {
;         const int mt = item / 8, nt = item % 8;
;         f32x4 acc[8][4]; zero_acc2(acc);
;         gemm_acc2(A + (size_t)mt * 256 * DFF, DFF, Wt + (size_t)nt * 128 * DFF, DFF, DFF, acc, lds);
;         resid_tile2(acc, P.out, mt * 256, nt * 128, gate);
;     }
	v_pk_fma_f32 v[132:133], v[124:125], v[196:197], v[132:133]
	v_pk_fma_f32 v[130:131], v[122:123], v[194:195], v[130:131]
	global_store_dwordx4 v[68:69], v[130:133], off offset:64
	s_waitcnt vmcnt(7)
	v_pk_fma_f32 v[136:137], v[112:113], v[196:197], v[136:137]
	v_pk_fma_f32 v[134:135], v[110:111], v[194:195], v[134:135]
	global_store_dwordx4 v[222:223], v[134:137], off offset:64
	s_waitcnt vmcnt(7)
	v_pk_fma_f32 v[140:141], v[100:101], v[196:197], v[140:141]
	v_pk_fma_f32 v[138:139], v[98:99], v[194:195], v[138:139]
	global_store_dwordx4 v[224:225], v[138:141], off offset:64
	s_waitcnt vmcnt(7)
	v_pk_fma_f32 v[144:145], v[88:89], v[196:197], v[144:145]
	v_pk_fma_f32 v[142:143], v[86:87], v[194:195], v[142:143]
	global_store_dwordx4 v[226:227], v[142:145], off offset:64
	s_waitcnt vmcnt(7)
	v_pk_fma_f32 v[164:165], v[76:77], v[196:197], v[164:165]
	v_pk_fma_f32 v[162:163], v[74:75], v[194:195], v[162:163]
	global_store_dwordx4 v[228:229], v[162:165], off offset:64
	s_waitcnt vmcnt(7)
	v_pk_fma_f32 v[168:169], v[64:65], v[196:197], v[168:169]
	v_pk_fma_f32 v[166:167], v[62:63], v[194:195], v[166:167]
	global_store_dwordx4 v[230:231], v[166:169], off offset:64
	s_waitcnt vmcnt(7)
	v_pk_fma_f32 v[172:173], v[48:49], v[196:197], v[172:173]
	v_pk_fma_f32 v[170:171], v[46:47], v[194:195], v[170:171]
	global_store_dwordx4 v[232:233], v[170:173], off offset:64
	s_waitcnt vmcnt(7)
	v_pk_fma_f32 v[176:177], v[36:37], v[196:197], v[176:177]
	v_pk_fma_f32 v[174:175], v[34:35], v[194:195], v[174:175]
	global_store_dwordx4 v[234:235], v[174:177], off offset:64
	global_load_dwordx4 v[190:193], v[102:103], off offset:128
	global_load_dwordx4 v[130:133], v[68:69], off offset:128
	global_load_dwordx4 v[134:137], v[222:223], off offset:128
	global_load_dwordx4 v[138:141], v[224:225], off offset:128
	global_load_dwordx4 v[142:145], v[226:227], off offset:128
	global_load_dwordx4 v[162:165], v[228:229], off offset:128
	global_load_dwordx4 v[166:169], v[230:231], off offset:128
	global_load_dwordx4 v[170:173], v[232:233], off offset:128
	global_load_dwordx4 v[174:177], v[234:235], off offset:128
	s_waitcnt vmcnt(7)
	v_pk_fma_f32 v[132:133], v[120:121], v[192:193], v[132:133]
	v_pk_fma_f32 v[130:131], v[118:119], v[190:191], v[130:131]
	global_store_dwordx4 v[68:69], v[130:133], off offset:128
	s_waitcnt vmcnt(7)
	v_pk_fma_f32 v[136:137], v[108:109], v[192:193], v[136:137]
	v_pk_fma_f32 v[134:135], v[106:107], v[190:191], v[134:135]
	global_store_dwordx4 v[222:223], v[134:137], off offset:128
	s_waitcnt vmcnt(7)
	v_pk_fma_f32 v[140:141], v[96:97], v[192:193], v[140:141]
	v_pk_fma_f32 v[138:139], v[94:95], v[190:191], v[138:139]
	global_store_dwordx4 v[224:225], v[138:141], off offset:128
	s_waitcnt vmcnt(7)
	v_pk_fma_f32 v[144:145], v[84:85], v[192:193], v[144:145]
	v_pk_fma_f32 v[142:143], v[82:83], v[190:191], v[142:143]
	global_store_dwordx4 v[226:227], v[142:145], off offset:128
	s_waitcnt vmcnt(7)
	v_pk_fma_f32 v[164:165], v[72:73], v[192:193], v[164:165]
	v_pk_fma_f32 v[162:163], v[70:71], v[190:191], v[162:163]
	global_store_dwordx4 v[228:229], v[162:165], off offset:128
	s_waitcnt vmcnt(7)
	v_pk_fma_f32 v[168:169], v[60:61], v[192:193], v[168:169]
	v_pk_fma_f32 v[166:167], v[58:59], v[190:191], v[166:167]
	global_store_dwordx4 v[230:231], v[166:169], off offset:128
	s_waitcnt vmcnt(7)
	v_pk_fma_f32 v[172:173], v[44:45], v[192:193], v[172:173]
	v_pk_fma_f32 v[170:171], v[42:43], v[190:191], v[170:171]
	global_store_dwordx4 v[232:233], v[170:173], off offset:128
	s_waitcnt vmcnt(7)
	v_pk_fma_f32 v[176:177], v[28:29], v[192:193], v[176:177]
	v_pk_fma_f32 v[174:175], v[26:27], v[190:191], v[174:175]
	global_store_dwordx4 v[234:235], v[174:177], off offset:128
	global_load_dwordx4 v[194:197], v[102:103], off offset:192
	global_load_dwordx4 v[130:133], v[68:69], off offset:192
	global_load_dwordx4 v[134:137], v[222:223], off offset:192
	global_load_dwordx4 v[138:141], v[224:225], off offset:192
	global_load_dwordx4 v[142:145], v[226:227], off offset:192
	global_load_dwordx4 v[162:165], v[228:229], off offset:192
	global_load_dwordx4 v[166:169], v[230:231], off offset:192
	global_load_dwordx4 v[170:173], v[232:233], off offset:192
	global_load_dwordx4 v[174:177], v[234:235], off offset:192
	s_waitcnt vmcnt(7)
	v_pk_fma_f32 v[132:133], v[56:57], v[196:197], v[132:133]
	v_pk_fma_f32 v[130:131], v[54:55], v[194:195], v[130:131]
	global_store_dwordx4 v[68:69], v[130:133], off offset:192
	s_waitcnt vmcnt(7)
	v_pk_fma_f32 v[136:137], v[32:33], v[196:197], v[136:137]
	v_pk_fma_f32 v[134:135], v[30:31], v[194:195], v[134:135]
	global_store_dwordx4 v[222:223], v[134:137], off offset:192
	s_waitcnt vmcnt(7)
	v_pk_fma_f32 v[140:141], v[24:25], v[196:197], v[140:141]
	v_pk_fma_f32 v[138:139], v[22:23], v[194:195], v[138:139]
	global_store_dwordx4 v[224:225], v[138:141], off offset:192
	s_waitcnt vmcnt(7)
	v_pk_fma_f32 v[144:145], v[20:21], v[196:197], v[144:145]
	v_pk_fma_f32 v[142:143], v[18:19], v[194:195], v[142:143]
	global_store_dwordx4 v[226:227], v[142:145], off offset:192
	s_waitcnt vmcnt(7)
	v_pk_fma_f32 v[164:165], v[16:17], v[196:197], v[164:165]
	v_pk_fma_f32 v[162:163], v[14:15], v[194:195], v[162:163]
	global_store_dwordx4 v[228:229], v[162:165], off offset:192
	s_waitcnt vmcnt(7)
	v_pk_fma_f32 v[168:169], v[12:13], v[196:197], v[168:169]
	v_pk_fma_f32 v[166:167], v[10:11], v[194:195], v[166:167]
	global_store_dwordx4 v[230:231], v[166:169], off offset:192
	s_waitcnt vmcnt(7)
	v_pk_fma_f32 v[172:173], v[8:9], v[196:197], v[172:173]
	v_pk_fma_f32 v[170:171], v[6:7], v[194:195], v[170:171]
	global_store_dwordx4 v[232:233], v[170:173], off offset:192
	s_waitcnt vmcnt(7)
	v_pk_fma_f32 v[176:177], v[4:5], v[196:197], v[176:177]
	v_pk_fma_f32 v[174:175], v[2:3], v[194:195], v[174:175]
	global_store_dwordx4 v[234:235], v[174:177], off offset:192
	s_cmpk_gt_i32 s21, 0x3ff
	s_cbranch_scc0 .LBB0_375

; __device__ __forceinline__ unsigned pack2(float a, float b) { const f32x2n v = {a, b}; const bf16x2n h = __builtin_convertvector(v, bf16x2n); return __builtin_bit_cast(unsigned, h); }
; __device__ void mx_mlstm(const Params& P, int l, int item, char* lds) {
;     ...
;             for (int it = 0; it < 2; ++it) {
;                 const int vi = tid + 256 * it, ii = vi >> 3, e = vi & 7, t = TROW(ii);
;                 float f[8];
;                 unpack8(*(const u32x4*)(pr + (size_t)t * PREST_LD + h * 64 + e * 8), f);
;                 *(u32x4*)(Q + ii * 72 + e * 8) = (u32x4){pack2(f[0] * 0.125f, f[1] * 0.125f), pack2(f[2] * 0.125f, f[3] * 0.125f), pack2(f[4] * 0.125f, f[5] * 0.125f), pack2(f[6] * 0.125f, f[7] * 0.125f)};
;                 const u32x4 kv = *(const u32x4*)(pr + (size_t)t * PREST_LD + 256 + h * 64 + e * 8);
;                 *(u32x4*)(KP + ii * 72 + e * 8) = kv;
;                 unpack8(kv, f);
;                 const float wi = WI[ii];
; #pragma unroll
;                 for (int x = 0; x < 8; ++x) KWT[(e * 8 + x) * 72 + ii] = f2bf(f[x] * wi);
;             }
; #pragma unroll
;             for (int it = 0; it < 4; ++it) {
;                 const int vi = tid + 256 * it, ii = vi >> 4, e = vi & 15, t = TROW(ii);
;                 const u32x4 vv = *(const u32x4*)(pr + (size_t)t * PREST_LD + 512 + h * 128 + e * 8);
;                 VT[(e * 8 + 0) * 72 + ii] = (bf16_t)(vv.x & 0xffff); VT[(e * 8 + 1) * 72 + ii] = (bf16_t)(vv.x >> 16);
;                 VT[(e * 8 + 2) * 72 + ii] = (bf16_t)(vv.y & 0xffff); VT[(e * 8 + 3) * 72 + ii] = (bf16_t)(vv.y >> 16);
;                 VT[(e * 8 + 4) * 72 + ii] = (bf16_t)(vv.z & 0xffff); VT[(e * 8 + 5) * 72 + ii] = (bf16_t)(vv.z >> 16);
;                 VT[(e * 8 + 6) * 72 + ii] = (bf16_t)(vv.w & 0xffff); VT[(e * 8 + 7) * 72 + ii] = (bf16_t)(vv.w >> 16);
;             }
.LBB0_476:
	s_or_b64 exec, exec, s[28:29]
	s_or_b32 s28, s97, 63
	v_sub_u32_e32 v0, s28, v86
	s_waitcnt vmcnt(7)
	v_add_u32_e32 v34, s21, v86
	v_cndmask_b32_e64 v0, v0, v34, s[38:39]
	s_waitcnt vmcnt(6)
	v_mad_i64_i32 v[38:39], s[26:27], v0, s3, v[60:61]
	global_load_dwordx4 v[34:37], v[38:39], off
	global_load_dwordx4 v[144:147], v[38:39], off offset:512
	v_sub_u32_e32 v132, s28, v87
	v_add_u32_e32 v133, s21, v87
	v_cndmask_b32_e64 v132, v132, v133, s[38:39]
	v_mad_i64_i32 v[134:135], s[26:27], v132, s3, v[60:61]
	global_load_dwordx4 v[148:151], v[134:135], off
	global_load_dwordx4 v[152:155], v[134:135], off offset:512
	v_sub_u32_e32 v132, s28, v88
	v_add_u32_e32 v133, s21, v88
	v_cndmask_b32_e64 v132, v132, v133, s[38:39]
	v_mad_i64_i32 v[136:137], s[26:27], v132, s3, v[62:63]
	global_load_dwordx4 v[156:159], v[136:137], off offset:1024
	v_sub_u32_e32 v132, s28, v90
	v_add_u32_e32 v133, s21, v90
	v_cndmask_b32_e64 v132, v132, v133, s[38:39]
	v_mad_i64_i32 v[138:139], s[26:27], v132, s3, v[62:63]
	global_load_dwordx4 v[160:163], v[138:139], off offset:1024
	v_sub_u32_e32 v132, s28, v92
	v_add_u32_e32 v133, s21, v92
	v_cndmask_b32_e64 v132, v132, v133, s[38:39]
	v_mad_i64_i32 v[140:141], s[26:27], v132, s3, v[62:63]
	global_load_dwordx4 v[164:167], v[140:141], off offset:1024
	v_sub_u32_e32 v132, s28, v94
	v_add_u32_e32 v133, s21, v94
	v_cndmask_b32_e64 v132, v132, v133, s[38:39]
	v_mad_i64_i32 v[142:143], s[26:27], v132, s3, v[62:63]
	global_load_dwordx4 v[168:171], v[142:143], off offset:1024
	s_waitcnt lgkmcnt(0)
	s_barrier
; __device__ __forceinline__ unsigned pack2(float a, float b) { const f32x2n v = {a, b}; const bf16x2n h = __builtin_convertvector(v, bf16x2n); return __builtin_bit_cast(unsigned, h); }
; __device__ void mx_mlstm(const Params& P, int l, int item, char* lds) {
;     ...
;             for (int it = 0; it < 2; ++it) {
;                 const int vi = tid + 256 * it, ii = vi >> 3, e = vi & 7, t = TROW(ii);
;                 float f[8];
;                 unpack8(*(const u32x4*)(pr + (size_t)t * PREST_LD + h * 64 + e * 8), f);
;                 *(u32x4*)(Q + ii * 72 + e * 8) = (u32x4){pack2(f[0] * 0.125f, f[1] * 0.125f), pack2(f[2] * 0.125f, f[3] * 0.125f), pack2(f[4] * 0.125f, f[5] * 0.125f), pack2(f[6] * 0.125f, f[7] * 0.125f)};
;                 const u32x4 kv = *(const u32x4*)(pr + (size_t)t * PREST_LD + 256 + h * 64 + e * 8);
;                 *(u32x4*)(KP + ii * 72 + e * 8) = kv;
;                 unpack8(kv, f);
;                 const float wi = WI[ii];
; #pragma unroll
;                 for (int x = 0; x < 8; ++x) KWT[(e * 8 + x) * 72 + ii] = f2bf(f[x] * wi);
;             }
; #pragma unroll
;             for (int it = 0; it < 4; ++it) {
;                 const int vi = tid + 256 * it, ii = vi >> 4, e = vi & 15, t = TROW(ii);
;                 const u32x4 vv = *(const u32x4*)(pr + (size_t)t * PREST_LD + 512 + h * 128 + e * 8);
;                 VT[(e * 8 + 0) * 72 + ii] = (bf16_t)(vv.x & 0xffff); VT[(e * 8 + 1) * 72 + ii] = (bf16_t)(vv.x >> 16);
;                 VT[(e * 8 + 2) * 72 + ii] = (bf16_t)(vv.y & 0xffff); VT[(e * 8 + 3) * 72 + ii] = (bf16_t)(vv.y >> 16);
;                 VT[(e * 8 + 4) * 72 + ii] = (bf16_t)(vv.z & 0xffff); VT[(e * 8 + 5) * 72 + ii] = (bf16_t)(vv.z >> 16);
;                 VT[(e * 8 + 6) * 72 + ii] = (bf16_t)(vv.w & 0xffff); VT[(e * 8 + 7) * 72 + ii] = (bf16_t)(vv.w >> 16);
;             }
;             __syncthreads();
;             f32x4 sacc[4];
; #pragma unroll
;             for (int st = 0; st < 4; ++st) sacc[st] = (f32x4){0.f, 0.f, 0.f, 0.f};
; #pragma unroll
;             for (int ks = 0; ks < 2; ++ks) {
;                 const bf16x8 qf = ldfrag(Q + i * 72 + ks * 32 + fq * 8);
; #pragma unroll
;                 for (int st = 0; st < 4; ++st) sacc[st] = mfma16(ldfrag(KP + (st * 16 + fr) * 72 + ks * 32 + fq * 8), qf, sacc[st]);
;             }
	v_add_u32_e32 v102, v70, v96
	v_mov_b32_e32 v103, 0
	s_waitcnt vmcnt(7)
	v_lshlrev_b32_e32 v40, 16, v34
	v_and_b32_e32 v41, 0xffff0000, v34
	v_pk_mul_f32 v[40:41], v[40:41], s[2:3] op_sel_hi:[1,0]
	s_nop 0
	v_cvt_pk_bf16_f32 v34, v40, v41
	v_lshlrev_b32_e32 v40, 16, v35
	v_and_b32_e32 v41, 0xffff0000, v35
	v_pk_mul_f32 v[40:41], v[40:41], s[2:3] op_sel_hi:[1,0]
	s_nop 0
	v_cvt_pk_bf16_f32 v35, v40, v41
	v_lshlrev_b32_e32 v40, 16, v36
	v_and_b32_e32 v41, 0xffff0000, v36
	v_pk_mul_f32 v[40:41], v[40:41], s[2:3] op_sel_hi:[1,0]
	s_nop 0
	v_cvt_pk_bf16_f32 v36, v40, v41
	v_lshlrev_b32_e32 v40, 16, v37
	v_and_b32_e32 v41, 0xffff0000, v37
	v_pk_mul_f32 v[40:41], v[40:41], s[2:3] op_sel_hi:[1,0]
	s_nop 0
	v_cvt_pk_bf16_f32 v37, v40, v41
	ds_write_b128 v56, v[34:37]
	s_waitcnt vmcnt(6)
	ds_write_b128 v56, v[144:147] offset:9216
	ds_read_b32 v41, v57
	v_lshlrev_b32_e32 v0, 16, v144
	v_and_b32_e32 v144, 0xffff0000, v144
	v_lshlrev_b32_e32 v38, 16, v145
	v_and_b32_e32 v145, 0xffff0000, v145
	s_waitcnt lgkmcnt(0)
	v_mul_f32_e32 v0, v41, v0
	v_cvt_pk_bf16_f32 v0, v0, s0
	ds_write_b16 v97, v0 offset:18432
	v_mul_f32_e32 v0, v41, v144
	v_cvt_pk_bf16_f32 v0, v0, s0
	ds_write_b16 v97, v0 offset:18576
	v_mul_f32_e32 v0, v41, v38
	v_cvt_pk_bf16_f32 v0, v0, s0
	ds_write_b16 v97, v0 offset:18720
	v_mul_f32_e32 v0, v41, v145
	v_lshlrev_b32_e32 v39, 16, v146
	v_cvt_pk_bf16_f32 v0, v0, s0
	ds_write_b16 v97, v0 offset:18864
	v_mul_f32_e32 v0, v41, v39
	v_and_b32_e32 v146, 0xffff0000, v146
	v_cvt_pk_bf16_f32 v0, v0, s0
	ds_write_b16 v97, v0 offset:19008
	v_mul_f32_e32 v0, v41, v146
	v_lshlrev_b32_e32 v40, 16, v147
	v_cvt_pk_bf16_f32 v0, v0, s0
	ds_write_b16 v97, v0 offset:19152
	v_mul_f32_e32 v0, v41, v40
	v_and_b32_e32 v147, 0xffff0000, v147
	v_cvt_pk_bf16_f32 v0, v0, s0
	ds_write_b16 v97, v0 offset:19296
	v_mul_f32_e32 v0, v41, v147
	v_cvt_pk_bf16_f32 v0, v0, s0
	ds_write_b16 v97, v0 offset:19440
	s_waitcnt vmcnt(5)
	v_lshlrev_b32_e32 v40, 16, v148
	v_and_b32_e32 v41, 0xffff0000, v148
	v_pk_mul_f32 v[40:41], v[40:41], s[2:3] op_sel_hi:[1,0]
	s_nop 0
	v_cvt_pk_bf16_f32 v148, v40, v41
	v_lshlrev_b32_e32 v40, 16, v149
	v_and_b32_e32 v41, 0xffff0000, v149
	v_pk_mul_f32 v[40:41], v[40:41], s[2:3] op_sel_hi:[1,0]
	s_nop 0
	v_cvt_pk_bf16_f32 v149, v40, v41
	v_lshlrev_b32_e32 v40, 16, v150
	v_and_b32_e32 v41, 0xffff0000, v150
	v_pk_mul_f32 v[40:41], v[40:41], s[2:3] op_sel_hi:[1,0]
	s_nop 0
	v_cvt_pk_bf16_f32 v150, v40, v41
	v_lshlrev_b32_e32 v40, 16, v151
	v_and_b32_e32 v41, 0xffff0000, v151
	v_pk_mul_f32 v[40:41], v[40:41], s[2:3] op_sel_hi:[1,0]
	s_nop 0
	v_cvt_pk_bf16_f32 v151, v40, v41
	ds_write_b128 v58, v[148:151]
	s_waitcnt vmcnt(4)
	ds_write_b128 v58, v[152:155] offset:9216
	ds_read_b32 v41, v59
	v_lshlrev_b32_e32 v0, 16, v152
	v_and_b32_e32 v152, 0xffff0000, v152
	v_lshlrev_b32_e32 v38, 16, v153
	v_and_b32_e32 v153, 0xffff0000, v153
	s_waitcnt lgkmcnt(0)
	v_mul_f32_e32 v0, v41, v0
	v_cvt_pk_bf16_f32 v0, v0, s0
	ds_write_b16 v98, v0 offset:18432
	v_mul_f32_e32 v0, v41, v152
	v_cvt_pk_bf16_f32 v0, v0, s0
	ds_write_b16 v98, v0 offset:18576
	v_mul_f32_e32 v0, v41, v38
	v_cvt_pk_bf16_f32 v0, v0, s0
	ds_write_b16 v98, v0 offset:18720
	v_mul_f32_e32 v0, v41, v153
	v_lshlrev_b32_e32 v39, 16, v154
	v_cvt_pk_bf16_f32 v0, v0, s0
	ds_write_b16 v98, v0 offset:18864
	v_mul_f32_e32 v0, v41, v39
	v_and_b32_e32 v154, 0xffff0000, v154
	v_cvt_pk_bf16_f32 v0, v0, s0
	ds_write_b16 v98, v0 offset:19008
	v_mul_f32_e32 v0, v41, v154
	v_lshlrev_b32_e32 v40, 16, v155
	v_cvt_pk_bf16_f32 v0, v0, s0
	ds_write_b16 v98, v0 offset:19152
	v_mul_f32_e32 v0, v41, v40
	v_and_b32_e32 v155, 0xffff0000, v155
	v_cvt_pk_bf16_f32 v0, v0, s0
	ds_write_b16 v98, v0 offset:19296
	v_mul_f32_e32 v0, v41, v155
	v_cvt_pk_bf16_f32 v0, v0, s0
	ds_write_b16 v98, v0 offset:19440
	s_waitcnt vmcnt(3)
	ds_write_b16 v89, v156 offset:27648
	ds_write_b16_d16_hi v89, v156 offset:27792
	ds_write_b16 v89, v157 offset:27936
	ds_write_b16_d16_hi v89, v157 offset:28080
	ds_write_b16 v89, v158 offset:28224
	ds_write_b16_d16_hi v89, v158 offset:28368
	ds_write_b16 v89, v159 offset:28512
	ds_write_b16_d16_hi v89, v159 offset:28656
	s_waitcnt vmcnt(2)
	ds_write_b16 v91, v160 offset:27648
	ds_write_b16_d16_hi v91, v160 offset:27792
	ds_write_b16 v91, v161 offset:27936
	ds_write_b16_d16_hi v91, v161 offset:28080
	ds_write_b16 v91, v162 offset:28224
	ds_write_b16_d16_hi v91, v162 offset:28368
	ds_write_b16 v91, v163 offset:28512
	ds_write_b16_d16_hi v91, v163 offset:28656
	s_waitcnt vmcnt(1)
	ds_write_b16 v93, v164 offset:27648
	ds_write_b16_d16_hi v93, v164 offset:27792
	ds_write_b16 v93, v165 offset:27936
	ds_write_b16_d16_hi v93, v165 offset:28080
	ds_write_b16 v93, v166 offset:28224
	ds_write_b16_d16_hi v93, v166 offset:28368
	ds_write_b16 v93, v167 offset:28512
	ds_write_b16_d16_hi v93, v167 offset:28656
	v_mov_b32_e32 v0, 0
	s_waitcnt vmcnt(0)
	ds_write_b16 v95, v168 offset:27648
	ds_write_b16_d16_hi v95, v168 offset:27792
	ds_write_b16 v95, v169 offset:27936
	ds_write_b16_d16_hi v95, v169 offset:28080
	ds_write_b16 v95, v170 offset:28224
	ds_write_b16_d16_hi v95, v170 offset:28368
	ds_write_b16 v95, v171 offset:28512
	ds_write_b16_d16_hi v95, v171 offset:28656
	s_waitcnt lgkmcnt(0)
	s_barrier
	ds_read_b128 v[42:45], v102 offset:11520
	ds_read_b128 v[46:49], v102 offset:13824
	ds_read_b128 v[34:37], v69
	ds_read_b128 v[38:41], v102 offset:9216
	s_waitcnt lgkmcnt(1)
	v_mfma_f32_16x16x32_bf16 v[104:107], v[46:49], v[34:37], 0
	ds_read_b128 v[46:49], v102 offset:16128
	s_waitcnt lgkmcnt(1)
	v_mfma_f32_16x16x32_bf16 v[38:41], v[38:41], v[34:37], 0
	v_mfma_f32_16x16x32_bf16 v[42:45], v[42:45], v[34:37], 0
	s_waitcnt lgkmcnt(0)
	v_mfma_f32_16x16x32_bf16 v[34:37], v[46:49], v[34:37], 0
	ds_read_b128 v[108:111], v69 offset:64
	ds_read_b128 v[46:49], v102 offset:9280
	ds_read2st64_b32 v[64:65], v52 offset0:254 offset1:255
	s_waitcnt lgkmcnt(1)
	v_mfma_f32_16x16x32_bf16 v[46:49], v[46:49], v[108:111], v[38:41]
	s_nop 2
	ds_read_b128 v[38:41], v102 offset:11584
	s_waitcnt lgkmcnt(0)
	v_mfma_f32_16x16x32_bf16 v[42:45], v[38:41], v[108:111], v[42:45]
	ds_read_b128 v[38:41], v102 offset:13888
	s_waitcnt lgkmcnt(0)
	v_mfma_f32_16x16x32_bf16 v[38:41], v[38:41], v[108:111], v[104:107]
	s_nop 2
	ds_read_b128 v[104:107], v102 offset:16192
	s_waitcnt lgkmcnt(0)
	v_mfma_f32_16x16x32_bf16 v[34:37], v[104:107], v[108:111], v[34:37]
	s_and_saveexec_b64 s[28:29], s[54:55]
	s_cbranch_execz .LBB0_506
	ds_read_b32 v103, v70 offset:64768
	s_waitcnt lgkmcnt(0)
	v_sub_f32_e32 v103, v103, v64
	v_mul_f32_e32 v103, 0x3fb8aa3b, v103
	v_exp_f32_e32 v103, v103
	s_nop 0
	v_mul_f32_e32 v103, v46, v103
	s_or_b64 exec, exec, s[28:29]
	v_mov_b32_e32 v46, 0
	s_and_saveexec_b64 s[28:29], s[56:57]
	s_cbranch_execnz .LBB0_507
